# E1 L0+L2: full-line LDS-DMA pieces (8 rows x 128B) with new swizzled LDS layout + dual k-half bases; plus coalesced epilogues (E1 x2, O3 L3)
# speedup vs baseline: 1.0031x; 1.0031x over previous
; __device__ __forceinline__ unsigned xb_ld(unsigned* p)              { return __hip_atomic_load(p, __ATOMIC_RELAXED, __HIP_MEMORY_SCOPE_AGENT); }
;     __device__ bool next(int i, Unit& u) const {
;         const long L = (long)i * G + c; if (L >= nwg) return false;
;         int wgid = (int)L; { const int q = nwg / NXCD, r = nwg % NXCD, xcd = wgid % NXCD, off = wgid / NXCD; wgid = (xcd < r ? xcd * (q + 1) : r * (q + 1) + (xcd - r) * q) + off; }
;         const int nig = WGM * nN, gid = wgid / nig, fm = gid * WGM, gsz = (nM - fm) < WGM ? (nM - fm) : WGM;
;         u.pm = fm + ((wgid % nig) % gsz); u.pn = (wgid % nig) / gsz; u.aux = 0; return true;
; __global__ void __launch_bounds__(512, 2) hybrid_fwd(Params p) {
;     ...
;     { unsigned mine = 0u, cnt = 0u;
; #pragma unroll
;       for (unsigned j = 0; j < 16; ++j) { const unsigned c = xb_ld(&xb.bar[XB_XCNT(j)]); cnt += (c > 0u) ? 1u : 0u; mine = (j == xb.x) ? c : mine; }
;       xb.nloc = __builtin_amdgcn_readfirstlane(mine > 0u ? mine : 1u); xb.nx = __builtin_amdgcn_readfirstlane(cnt > 0u ? cnt : 1u); }
.LBB0_200:
	s_or_b64 exec, exec, s[4:5]
	v_mov_b32_e32 v0, 0x180000
	s_barrier
	global_load_dword v1, v0, s[86:87] offset:1024 sc1
	global_load_dword v2, v0, s[86:87] offset:1280 sc1
	global_load_dword v3, v0, s[86:87] offset:1536 sc1
	v_mov_b32_e32 v4, 0x181000
	global_load_dword v5, v0, s[86:87] offset:1792 sc1
	global_load_dword v6, v0, s[86:87] offset:2048 sc1
	global_load_dword v7, v0, s[86:87] offset:2304 sc1
	global_load_dword v8, v0, s[86:87] offset:2560 sc1
	global_load_dword v9, v0, s[86:87] offset:2816 sc1
	global_load_dword v10, v0, s[86:87] offset:3072 sc1
	global_load_dword v11, v0, s[86:87] offset:3328 sc1
	global_load_dword v12, v0, s[86:87] offset:3584 sc1
	global_load_dword v13, v0, s[86:87] offset:3840 sc1
	global_load_dword v14, v4, s[86:87] sc1
	global_load_dword v15, v4, s[86:87] offset:256 sc1
	global_load_dword v16, v4, s[86:87] offset:512 sc1
	s_cmp_eq_u32 s73, 0
	global_load_dword v0, v4, s[86:87] offset:768 sc1
	s_cselect_b64 vcc, -1, 0
	s_cmp_eq_u32 s73, 1
	s_mov_b64 s[0:1], s[74:75]
	s_load_dwordx2 s[36:37], s[0:1], 0x90
	s_waitcnt lgkmcnt(0)
	s_barrier
	s_waitcnt vmcnt(15)
	v_cndmask_b32_e32 v4, 0, v1, vcc
	s_waitcnt vmcnt(14)
	v_cmp_ne_u32_e32 vcc, 0, v2
	s_waitcnt vmcnt(13)
	v_cmp_ne_u32_e64 s[4:5], 0, v3
	v_cndmask_b32_e64 v17, 0, 1, vcc
	s_nop 0
	v_cndmask_b32_e64 v18, 0, 1, s[4:5]
	s_waitcnt vmcnt(11)
	v_cmp_ne_u32_e64 s[4:5], 0, v6
	s_cselect_b64 vcc, -1, 0
	s_cmp_eq_u32 s73, 2
	v_cndmask_b32_e64 v19, 0, 1, s[4:5]
	s_waitcnt vmcnt(9)
	v_cmp_ne_u32_e64 s[4:5], 0, v8
	v_cndmask_b32_e32 v2, v4, v2, vcc
	s_cselect_b64 vcc, -1, 0
	v_cndmask_b32_e64 v20, 0, 1, s[4:5]
	s_waitcnt vmcnt(7)
	v_cmp_ne_u32_e64 s[4:5], 0, v10
	v_cndmask_b32_e32 v2, v2, v3, vcc
	v_cmp_ne_u32_e32 vcc, 0, v5
	v_cndmask_b32_e64 v21, 0, 1, s[4:5]
	s_waitcnt vmcnt(5)
	v_cmp_ne_u32_e64 s[4:5], 0, v12
	s_cmp_eq_u32 s73, 3
	s_nop 0
	v_cndmask_b32_e64 v22, 0, 1, s[4:5]
	s_waitcnt vmcnt(3)
	v_cmp_ne_u32_e64 s[4:5], 0, v14
	s_nop 1
	v_cndmask_b32_e64 v23, 0, 1, s[4:5]
	v_cmp_ne_u32_e64 s[4:5], 0, v1
	s_nop 1
	v_addc_co_u32_e64 v1, s[4:5], 0, v17, s[4:5]
	v_addc_co_u32_e32 v1, vcc, v1, v18, vcc
	s_cselect_b64 vcc, -1, 0
	s_cmp_eq_u32 s73, 4
	v_cndmask_b32_e32 v2, v2, v5, vcc
	s_cselect_b64 vcc, -1, 0
	s_cmp_eq_u32 s73, 5
	v_cndmask_b32_e32 v2, v2, v6, vcc
	s_cselect_b64 vcc, -1, 0
	s_cmp_eq_u32 s73, 6
	v_cndmask_b32_e32 v2, v2, v7, vcc
	s_cselect_b64 vcc, -1, 0
	s_cmp_eq_u32 s73, 7
	v_cmp_ne_u32_e64 s[4:5], 0, v7
	v_cndmask_b32_e32 v2, v2, v8, vcc
	s_cselect_b64 vcc, -1, 0
	s_cmp_eq_u32 s73, 8
	v_addc_co_u32_e64 v1, s[4:5], v1, v19, s[4:5]
	v_cndmask_b32_e32 v2, v2, v9, vcc
	s_cselect_b64 vcc, -1, 0
	s_cmp_eq_u32 s73, 9
	v_cmp_ne_u32_e64 s[4:5], 0, v9
	v_cndmask_b32_e32 v2, v2, v10, vcc
	s_cselect_b64 vcc, -1, 0
	s_cmp_eq_u32 s73, 10
	v_addc_co_u32_e64 v1, s[4:5], v1, v20, s[4:5]
	v_cndmask_b32_e32 v2, v2, v11, vcc
	s_cselect_b64 vcc, -1, 0
	s_cmp_eq_u32 s73, 11
	v_cmp_ne_u32_e64 s[4:5], 0, v11
	v_cndmask_b32_e32 v2, v2, v12, vcc
	s_cselect_b64 vcc, -1, 0
	s_cmp_eq_u32 s73, 12
	v_addc_co_u32_e64 v1, s[4:5], v1, v21, s[4:5]
	v_cndmask_b32_e32 v2, v2, v13, vcc
	s_cselect_b64 vcc, -1, 0
	s_cmp_eq_u32 s73, 13
	v_cmp_ne_u32_e64 s[4:5], 0, v13
	v_cndmask_b32_e32 v2, v2, v14, vcc
	s_cselect_b64 vcc, -1, 0
	v_addc_co_u32_e64 v1, s[4:5], v1, v22, s[4:5]
	s_waitcnt vmcnt(2)
	v_cndmask_b32_e32 v2, v2, v15, vcc
	s_waitcnt vmcnt(1)
	v_cmp_ne_u32_e32 vcc, 0, v16
	s_cmp_eq_u32 s73, 14
	v_cmp_ne_u32_e64 s[4:5], 0, v15
	v_cndmask_b32_e64 v3, 0, 1, vcc
	s_cselect_b64 vcc, -1, 0
	v_addc_co_u32_e64 v1, s[4:5], v1, v23, s[4:5]
	v_cndmask_b32_e32 v2, v2, v16, vcc
	s_waitcnt vmcnt(0)
	v_cmp_ne_u32_e32 vcc, 0, v0
	s_cmp_eq_u32 s73, 15
	v_mov_b32_e32 v10, v254
	v_addc_co_u32_e32 v1, vcc, v1, v3, vcc
	s_cselect_b64 vcc, -1, 0
	s_add_u32 s12, s36, 0x2e00000
	s_addc_u32 s13, s37, 0
	s_add_u32 s30, s36, 0x200000
	v_cndmask_b32_e32 v0, v2, v0, vcc
	s_addc_u32 s31, s37, 0
	v_max_u32_e32 v0, 1, v0
	s_add_u32 s8, s36, 0xa00000
	v_readfirstlane_b32 s0, v0
	v_max_u32_e32 v0, 1, v1
	s_addc_u32 s9, s37, 0
	v_writelane_b32 v255, s0, 1
	v_readfirstlane_b32 s0, v0
	s_cmpk_lt_i32 s33, 0xa00
	s_nop 0
	v_writelane_b32 v255, s0, 2
	s_cselect_b64 s[0:1], -1, 0
	v_writelane_b32 v255, s0, 3
	v_readfirstlane_b32 s5, v10
	s_and_b64 vcc, exec, s[0:1]
	v_writelane_b32 v255, s1, 4
	s_cbranch_vccz .LBB0_235
; #define PG8_STAGE(bufoff, gbase, voff) do { _Pragma("unroll") for (int _i = 0; _i < 2; ++_i) \
;         __builtin_amdgcn_global_load_lds((const unsigned*)((const char*)(gbase) + (voff)[_i]), (LAS unsigned*)(lds + (bufoff) + ldsw + _i * 8192), 16, 0, 0); } while (0)
; template <class Epi, class Sched>
; __device__ __forceinline__ void gemm_phase(LAS unsigned char* lds, const int K, const int lda, const int ldb, const Sched& S, const Epi& E) {
;     ...
;     const int wid = __builtin_amdgcn_readfirstlane(tid >> 6), lane = tid & 63, wr = wid >> 2, wc = wid & 3, fr = lane & 15, fq = lane >> 4;
;     const int nt = K / BK;
;     unsigned voffA[2], voffB[2];
; #pragma unroll
;     for (int i = 0; i < 2; ++i) { int R, C; stage_rc(tid * 16 + i * 8192, R, C); const int Rb = (R & ~31) + perm32(R & 31);
;         voffA[i] = (unsigned)(R * lda + C) * 2u; voffB[i] = (unsigned)(Rb * ldb + C) * 2u; }
;     const size_t kstep = (size_t)(BK * 2);
;     const size_t hA = (size_t)HALF * lda * 2, hB = (size_t)HALF * ldb * 2;
;     const unsigned ldsw = (unsigned)wid * 1024u;
;     const int aoff = lds_byte(wr * 64 + fr, fq * 8), boff = lds_byte(wc * 32 + fr, fq * 8);
;     ...
;     Unit cur, nxt; int ui = 0;
;     if (!S.next(0, cur)) return;
;     f32x4 acc[2][2][4][2];
; #pragma unroll
;     for (int a = 0; a < 2; ++a)
; #pragma unroll
;         for (int b = 0; b < 2; ++b)
; #pragma unroll
;             for (int m = 0; m < 4; ++m)
; #pragma unroll
;                 for (int n = 0; n < 2; ++n) acc[a][b][m][n] = (f32x4){0.f, 0.f, 0.f, 0.f};
;     bf16x8 At[4][2], B0[2][2], B1[2][2];
;     const char* cA = S.aptr(cur); const char* cB = S.bptr(cur);
;     PG8_STAGE(PG8_SB(0, 0), cB, voffB); PG8_STAGE(PG8_SB(0, 1), cB + hB, voffB); PG8_STAGE(PG8_SA(0, 0), cA, voffA); PG8_STAGE(PG8_SA(0, 1), cA + hA, voffA);
	v_lshlrev_b32_e32 v0, 4, v10
	v_add_u32_e32 v1, 0x2000, v0
	v_ashrrev_i32_e32 v2, 31, v1
	v_lshrrev_b32_e32 v2, 22, v2
	v_add_u32_e32 v2, v1, v2
	v_ashrrev_i32_e32 v8, 10, v2
	v_mul_i32_i24_e32 v2, 0x400, v8
	v_sub_u32_e32 v1, v1, v2
	v_lshrrev_b32_e32 v2, 4, v1
	v_bitop3_b32 v1, v2, v1, 32 bitop3:0x6c
	v_ashrrev_i32_e32 v2, 31, v1
	v_lshrrev_b32_e32 v2, 26, v2
	v_add_u32_e32 v2, v1, v2
	v_lshlrev_b32_e32 v3, 3, v8
	v_ashrrev_i32_e32 v9, 6, v2
	v_and_b32_e32 v3, -16, v3
	v_add_u32_e32 v3, v9, v3
	v_and_b32_e32 v4, 3, v9
	s_mov_b32 s0, 0xfffe0
	v_lshrrev_b32_e32 v5, 2, v3
	v_lshlrev_b32_e32 v6, 1, v3
	v_and_b32_e32 v2, 0xc0, v2
	v_and_or_b32 v4, v3, s0, v4
	v_and_b32_e32 v5, 4, v5
	v_and_b32_e32 v6, 24, v6
	v_sub_u32_e32 v1, v1, v2
	v_mov_b32_e32 v2, 1
	v_or3_b32 v4, v4, v5, v6
	v_lshlrev_b32_e32 v5, 5, v8
	v_ashrrev_i16_sdwa v1, v2, sext(v1) dst_sel:DWORD dst_unused:UNUSED_PAD src0_sel:DWORD src1_sel:BYTE_0
	v_and_b32_e32 v5, 32, v5
	v_bfe_i32 v11, v1, 0, 16
	v_add_lshl_u32 v1, v5, v11, 1
	v_and_b32_e32 v242, 63, v254
	v_lshrrev_b32_e32 v243, 6, v254
	v_lshrrev_b32_e32 v244, 3, v242
	v_lshl_add_u32 v245, v243, 3, v244
	v_and_b32_e32 v246, 1, v243
	v_bfe_u32 v247, v242, 4, 2
	v_lshl_add_u32 v247, v246, 2, v247
	v_and_b32_e32 v237, 7, v242
	v_xor_b32_e32 v247, v237, v247
	v_lshlrev_b32_e32 v247, 4, v247
	v_lshl_add_u32 v236, v245, 12, v247
	v_add_u32_e32 v237, 0x40000, v236
	v_lshrrev_b32_e32 v245, 5, v242
	v_lshlrev_b32_e32 v245, 3, v245
	v_lshl_add_u32 v245, v246, 4, v245
	v_bfe_u32 v246, v243, 1, 1
	v_lshl_add_u32 v245, v246, 2, v245
	v_and_b32_e32 v246, 3, v244
	v_add_u32_e32 v245, v245, v246
	v_lshrrev_b32_e32 v246, 2, v243
	v_lshl_add_u32 v245, v246, 5, v245
	v_lshl_add_u32 v238, v245, 12, v247
	v_add_u32_e32 v239, 0x40000, v238
	v_and_b32_e32 v242, 15, v254
	v_bfe_u32 v244, v254, 4, 2
	v_bfe_u32 v245, v254, 1, 3
	v_xor_b32_e32 v244, v244, v245
	v_lshlrev_b32_e32 v244, 4, v244
	v_lshl_add_u32 v244, v242, 7, v244
	v_lshrrev_b32_e32 v245, 8, v254
	v_lshl_add_u32 v240, v245, 13, v244
	v_and_b32_e32 v245, 3, v243
	v_lshl_add_u32 v241, v245, 13, v244
	v_mov_b32_e32 v128, v239
	v_mov_b32_e32 v130, v237
	v_bfe_i32 v1, v10, 27, 1
	v_lshrrev_b32_e32 v1, 22, v1
	v_add_u32_e32 v1, v0, v1
	v_and_b32_e32 v1, 0xfffffc00, v1
	v_sub_u32_e32 v0, v0, v1
	v_lshrrev_b32_e32 v1, 4, v0
	v_ashrrev_i32_e32 v3, 31, v10
	v_bitop3_b32 v0, v1, v0, 32 bitop3:0x6c
	v_lshrrev_b32_e32 v3, 26, v3
	v_ashrrev_i32_e32 v1, 31, v0
	v_add_u32_e32 v3, v10, v3
	v_lshrrev_b32_e32 v1, 26, v1
	v_ashrrev_i32_e32 v13, 6, v3
	v_add_u32_e32 v1, v0, v1
	v_lshlrev_b32_e32 v3, 3, v13
	v_ashrrev_i32_e32 v12, 6, v1
	v_and_b32_e32 v3, -16, v3
	v_add_u32_e32 v3, v12, v3
	v_and_b32_e32 v4, 3, v12
	s_ashr_i32 s14, s33, 31
	v_and_or_b32 v4, v3, s0, v4
	s_lshr_b32 s0, s14, 29
	s_add_i32 s0, s33, s0
	s_ashr_i32 s18, s5, 6
	s_ashr_i32 s1, s0, 3
	s_and_b32 s0, s0, -8
	s_ashr_i32 s19, s5, 8
	s_lshl_b32 s2, s18, 10
	s_sub_i32 s0, s33, s0
	s_cmp_lt_i32 s0, 0
	s_movk_i32 s15, 0x141
	s_cselect_b32 s4, s15, 0x140
	s_mul_i32 s0, s4, s0
	s_add_i32 s0, s0, s1
	s_mul_hi_i32 s1, s0, 0x66666667
	s_lshr_b32 s4, s1, 31
	s_ashr_i32 s1, s1, 6
	s_add_i32 s1, s1, s4
	s_lshl_b32 s6, s1, 3
	s_mulk_i32 s1, 0xa0
	s_sub_i32 s0, s0, s1
	s_sext_i32_i16 s1, s0
	s_bfe_u32 s1, s1, 0x3001c
	s_add_i32 s1, s0, s1
	s_sext_i32_i16 s4, s1
	s_and_b32 s1, s1, 0xfff8
	s_sub_i32 s0, s0, s1
	s_sext_i32_i16 s0, s0
	v_lshrrev_b32_e32 v5, 2, v3
	v_lshlrev_b32_e32 v6, 1, v3
	v_and_b32_e32 v1, 0xc0, v1
	s_lshr_b32 s4, s4, 3
	s_add_i32 s6, s6, s0
	v_and_b32_e32 v5, 4, v5
	v_and_b32_e32 v6, 24, v6
	v_sub_u32_e32 v0, v0, v1
	s_ashr_i32 s7, s6, 31
	s_bfe_i64 s[0:1], s[4:5], 0x100000
	v_or3_b32 v4, v4, v5, v6
	v_lshlrev_b32_e32 v5, 5, v13
	v_ashrrev_i16_sdwa v0, v2, sext(v0) dst_sel:DWORD dst_unused:UNUSED_PAD src0_sel:DWORD src1_sel:BYTE_0
	s_lshl_b64 s[10:11], s[6:7], 20
	s_lshl_b64 s[0:1], s[0:1], 20
	v_and_b32_e32 v5, 32, v5
	v_bfe_i32 v14, v0, 0, 16
	s_add_u32 s54, s8, s0
	v_add_lshl_u32 v0, v5, v14, 1
	s_addc_u32 s55, s9, s1
	s_add_i32 s1, s2, 0
	v_mov_b32_e32 v132, v238
	s_add_i32 m0, s1, 0x10000
	v_mov_b32_e32 v134, v236
	global_load_lds_dwordx4 v132, s[54:55]
	s_add_i32 m0, s1, 0x12000
	s_add_u32 s20, s54, 0x80000
	global_load_lds_dwordx4 v128, s[54:55]
	s_addc_u32 s21, s55, 0
	s_add_i32 m0, s1, 0x14000
	v_mov_b32_e32 v137, 0
	global_load_lds_dwordx4 v132, s[20:21]
	s_add_i32 m0, s1, 0x16000
	s_add_u32 s56, s12, s10
	s_addc_u32 s57, s13, s11
	s_add_i32 s17, s1, 0x2000
	global_load_lds_dwordx4 v128, s[20:21]
	s_mov_b32 m0, s1
	s_add_u32 s10, s56, 0x80000
	global_load_lds_dwordx4 v134, s[56:57]
	s_mov_b32 m0, s17
	s_addc_u32 s11, s57, 0
	s_add_i32 s29, s1, 0x4000
	global_load_lds_dwordx4 v130, s[56:57]
	s_mov_b32 m0, s29
	s_add_i32 s34, s1, 0x6000
	global_load_lds_dwordx4 v134, s[10:11]
	s_mov_b32 m0, s34
	v_mov_b32_e32 v133, v137
	global_load_lds_dwordx4 v130, s[10:11]
	v_mov_b32_e32 v129, v137
	v_mov_b32_e32 v135, v137
	v_mov_b32_e32 v131, v137
	s_cmp_eq_u32 s19, 1
	v_lshl_add_u64 v[6:7], s[54:55], 0, v[132:133]
	v_lshl_add_u64 v[4:5], s[54:55], 0, v[128:129]
	v_lshl_add_u64 v[0:1], s[56:57], 0, v[134:135]
	s_cselect_b64 s[10:11], -1, 0
	s_cmp_lg_u32 s19, 1
	v_lshl_add_u64 v[2:3], s[56:57], 0, v[130:131]
	s_cbranch_scc1 .LBB0_203
	s_barrier
; #define PG8_STAGE(bufoff, gbase, voff) do { _Pragma("unroll") for (int _i = 0; _i < 2; ++_i) \
;         __builtin_amdgcn_global_load_lds((const unsigned*)((const char*)(gbase) + (voff)[_i]), (LAS unsigned*)(lds + (bufoff) + ldsw + _i * 8192), 16, 0, 0); } while (0)
; #define PG8_WAIT_V(n) asm volatile("s_waitcnt vmcnt(" #n ")" ::: "memory")
; #define PG8_BAR __builtin_amdgcn_s_barrier()
; template <class Epi, class Sched>
; __device__ __forceinline__ void gemm_phase(LAS unsigned char* lds, const int K, const int lda, const int ldb, const Sched& S, const Epi& E) {
;     ...
;     const unsigned ldsw = (unsigned)wid * 1024u;
;     const int aoff = lds_byte(wr * 64 + fr, fq * 8), boff = lds_byte(wc * 32 + fr, fq * 8);
;     ...
;     Unit cur, nxt; int ui = 0;
;     if (!S.next(0, cur)) return;
;     f32x4 acc[2][2][4][2];
; #pragma unroll
;     for (int a = 0; a < 2; ++a)
; #pragma unroll
;         for (int b = 0; b < 2; ++b)
; #pragma unroll
;             for (int m = 0; m < 4; ++m)
; #pragma unroll
;                 for (int n = 0; n < 2; ++n) acc[a][b][m][n] = (f32x4){0.f, 0.f, 0.f, 0.f};
;     bf16x8 At[4][2], B0[2][2], B1[2][2];
;     const char* cA = S.aptr(cur); const char* cB = S.bptr(cur);
;     PG8_STAGE(PG8_SB(0, 0), cB, voffB); PG8_STAGE(PG8_SB(0, 1), cB + hB, voffB); PG8_STAGE(PG8_SA(0, 0), cA, voffA); PG8_STAGE(PG8_SA(0, 1), cA + hA, voffA);
;     if (wr == 1) PG8_BAR;
;     PG8_WAIT_V(2); PG8_BAR;
;     PG8_STAGE(PG8_SB(1, 0), cB + kstep, voffB); PG8_STAGE(PG8_SA(1, 0), cA + kstep, voffA); PG8_STAGE(PG8_SB(1, 1), cB + hB + kstep, voffB);
;     PG8_WAIT_V(6); PG8_BAR;
.LBB0_203:
	v_and_b32_e32 v157, 15, v10
	v_and_b32_e32 v17, 48, v10
	v_lshlrev_b32_e32 v18, 2, v10
	s_mov_b64 s[22:23], 0x80
	s_sext_i32_i16 s0, s4
	s_and_b32 s4, s18, 3
	s_lshl_b32 s7, s19, 13
	v_lshl_or_b32 v17, v157, 6, v17
	v_and_b32_e32 v18, 32, v18
	s_add_i32 m0, s1, 0x18000
	v_lshl_add_u64 v[6:7], v[6:7], 0, s[22:23]
	s_lshl_b32 s35, s19, 6
	v_bitop3_b32 v19, v17, s7, v18 bitop3:0xde
	s_lshl_b32 s7, s4, 5
	s_lshl_b32 s19, s4, 12
	s_waitcnt vmcnt(2)
	s_barrier
	global_load_lds_dwordx4 v[6:7], off
	v_lshl_add_u64 v[4:5], v[4:5], 0, s[22:23]
	s_add_i32 m0, s1, 0x1a000
	s_add_i32 s38, s1, 0x8000
	s_add_i32 s39, s1, 0xa000
	global_load_lds_dwordx4 v[4:5], off
	v_lshl_add_u64 v[0:1], v[0:1], 0, s[22:23]
	s_mov_b32 m0, s38
	s_add_u32 s24, s54, 0x80080
	global_load_lds_dwordx4 v[0:1], off
	v_lshl_add_u64 v[0:1], v[2:3], 0, s[22:23]
	s_mov_b32 m0, s39
	s_addc_u32 s25, s55, 0
	global_load_lds_dwordx4 v[0:1], off
	s_add_i32 m0, s1, 0x1c000
	v_lshl_add_u64 v[0:1], s[24:25], 0, v[132:133]
	global_load_lds_dwordx4 v[0:1], off
	v_lshl_add_u64 v[0:1], s[24:25], 0, v[128:129]
	s_add_i32 m0, s1, 0x1e000
	s_cmpk_lt_u32 s5, 0x100
	global_load_lds_dwordx4 v[0:1], off
	v_lshlrev_b32_e32 v26, 15, v8
	s_cselect_b64 s[24:25], -1, 0
	s_lshl_b32 s5, s18, 12
	v_and_b32_e32 v26, 0xffff0000, v26
	s_add_i32 s5, s5, 0
	v_lshl_add_u32 v9, v9, 12, v26
	v_and_b32_e32 v8, 1, v8
	s_add_i32 s5, s5, 0x20000
	v_lshl_or_b32 v8, v8, 6, v9
	s_add_u32 s41, s36, 0x1ce00000
	v_lshlrev_b32_e32 v0, 1, v10
	v_mov_b32_e32 v138, v237
	v_lshlrev_b32_e32 v8, 15, v13
	v_bfe_u32 v15, v10, 4, 2
	s_addc_u32 s62, s37, 0
	v_and_b32_e32 v0, 14, v0
	v_bfe_u32 v2, v10, 3, 1
	v_and_b32_e32 v8, 0xffff0000, v8
	s_add_u32 s63, s36, 0x14e00000
	v_add_u32_e32 v0, s5, v0
	v_bitop3_b32 v4, v2, v15, 2 bitop3:0x36
	v_lshl_add_u32 v8, v12, 12, v8
	v_and_b32_e32 v9, 1, v13
	s_addc_u32 s64, s37, 0
	v_xor_b32_e32 v3, v2, v15
	v_lshl_add_u32 v5, v4, 4, v0
	v_bitop3_b32 v4, v2, v15, 4 bitop3:0x36
	v_bitop3_b32 v2, v2, v15, 6 bitop3:0x36
	v_lshl_or_b32 v8, v9, 6, v8
	v_and_b32_e32 v159, 63, v10
	v_lshlrev_b32_e32 v16, 3, v15
	s_add_u32 s65, s36, 0xae00000
	v_lshlrev_b32_e32 v1, 10, v15
	v_lshl_add_u32 v15, v2, 4, v0
	v_and_b32_e32 v2, 7, v10
	v_bfe_u32 v10, v10, 3, 3
	v_mov_b32_e32 v140, v236
	v_mbcnt_lo_u32_b32 v8, -1, 0
	v_mov_b32_e32 v161, v241
	s_waitcnt vmcnt(6)
	s_addc_u32 s66, s37, 0
	s_lshl_b32 s4, s4, 21
	v_lshl_add_u32 v3, v3, 4, v0
	v_lshl_add_u32 v7, v4, 4, v0
	v_lshlrev_b32_e32 v0, 3, v2
	v_lshl_add_u32 v17, v10, 7, s5
	v_lshlrev_b32_e32 v18, 4, v2
	v_lshlrev_b32_e32 v2, 15, v10
	v_or_b32_e32 v4, 8, v10
	v_or_b32_e32 v6, 16, v10
	v_or_b32_e32 v10, 24, v10
	v_mbcnt_hi_u32_b32 v8, -1, v8
	v_lshl_add_u32 v20, v4, 7, s5
	v_xor_b32_e32 v21, 16, v18
	v_lshlrev_b32_e32 v4, 15, v4
	v_lshl_add_u32 v22, v6, 7, s5
	v_xor_b32_e32 v23, 32, v18
	v_lshlrev_b32_e32 v6, 15, v6
	v_lshl_add_u32 v24, v10, 7, s5
	v_xor_b32_e32 v25, 48, v18
	v_lshlrev_b32_e32 v10, 15, v10
	s_or_b32 s5, s4, 0x100000
	s_add_i32 s68, 0, 0x10000
	s_add_i32 s69, 0, 0x14000
	v_and_or_b32 v8, v8, 64, v157
	s_mov_b32 s21, 0
	s_ashr_i32 s67, s3, 31
	v_mov_b32_e32 v139, v137
	v_mov_b32_e32 v141, v137
	s_mov_b64 s[26:27], 0x100
	v_mov_b32_e32 v163, v240
	v_lshlrev_b32_e32 v165, 2, v8
	s_mov_b32 s28, 0x3a000000
	s_mov_b32 s70, 0x800000
	v_lshlrev_b32_e32 v136, 1, v0
	v_add_u32_e32 v167, v3, v1
	v_add_u32_e32 v169, v5, v1
	v_add_u32_e32 v171, v7, v1
	v_add_u32_e32 v173, v15, v1
	s_lshl_b32 s42, s4, 1
	v_add_u32_e32 v184, v17, v18
	v_lshlrev_b32_e32 v142, 1, v2
	v_add_u32_e32 v185, v20, v21
	v_lshlrev_b32_e32 v144, 1, v4
	v_add_u32_e32 v186, v22, v23
	v_lshlrev_b32_e32 v146, 1, v6
	v_add_u32_e32 v187, v24, v25
	v_lshlrev_b32_e32 v148, 1, v10
	s_lshl_b32 s44, s5, 1
	s_lshl_b32 s71, s7, 1
	v_lshlrev_b32_e32 v150, 1, v16
	v_mov_b64_e32 v[152:153], 0xa00
	v_mov_b64_e32 v[154:155], 0x9ff
	v_add_u32_e32 v188, s68, v161
	v_add_u32_e32 v189, 0x11000, v161
	v_mov_b32_e32 v156, 0x358637bd
	s_mov_b32 s72, 0
	s_barrier
	s_branch .LBB0_206

; #define PG8_STAGE(bufoff, gbase, voff) do { _Pragma("unroll") for (int _i = 0; _i < 2; ++_i) \
;         __builtin_amdgcn_global_load_lds((const unsigned*)((const char*)(gbase) + (voff)[_i]), (LAS unsigned*)(lds + (bufoff) + ldsw + _i * 8192), 16, 0, 0); } while (0)
; #define PG8_LDA(dst, b, h) do { _Pragma("unroll") for (int m = 0; m < 4; ++m) _Pragma("unroll") for (int k = 0; k < 2; ++k) dst[m][k] = *(const LAS bf16x8*)(lds + PG8_SA(b, h) + aoff + m * 2048 + k * 1024); } while (0)
; #define PG8_LDB(dst, b, h) do { _Pragma("unroll") for (int n = 0; n < 2; ++n) _Pragma("unroll") for (int k = 0; k < 2; ++k) dst[n][k] = *(const LAS bf16x8*)(lds + PG8_SB(b, h) + boff + n * 2048 + k * 1024); } while (0)
; #define PG8_MMA(ai, bj, At, Bt) do { __builtin_amdgcn_s_setprio(1); _Pragma("unroll") for (int m = 0; m < 4; ++m) _Pragma("unroll") for (int n = 0; n < 2; ++n) _Pragma("unroll") for (int k = 0; k < 2; ++k) \
;         acc[ai][bj][m][n] = __builtin_amdgcn_mfma_f32_16x16x32_bf16(Bt[n][k], At[m][k], acc[ai][bj][m][n], 0, 0, 0); __builtin_amdgcn_s_setprio(0); } while (0)
; #define PG8_WAIT_V(n) asm volatile("s_waitcnt vmcnt(" #n ")" ::: "memory")
; #define PG8_WAIT_L(n) asm volatile("s_waitcnt lgkmcnt(" #n ")" ::: "memory")
; #define PG8_BAR __builtin_amdgcn_s_barrier()
; #define PG8_SCHED __builtin_amdgcn_sched_barrier(0)
; template <class Epi, class Sched>
; __device__ __forceinline__ void gemm_phase(LAS unsigned char* lds, const int K, const int lda, const int ldb, const Sched& S, const Epi& E) {
;     ...
;             PG8_LDB(B0, 0, 0); PG8_LDB(B1, 0, 1); PG8_SCHED; PG8_LDA(At, 0, 0); PG8_STAGE(PG8_SA(1, 1), a1 + hA, voffA);
;             PG8_WAIT_V(8); PG8_WAIT_L(0); PG8_BAR; PG8_MMA(0, 0, At, B0); PG8_MMA(0, 1, At, B1); PG8_BAR; PG8_SCHED;
;     ...
;         for (int a = 0; a < 2; ++a)
; #pragma unroll
;             for (int b = 0; b < 2; ++b)
; #pragma unroll
;                 for (int m = 0; m < 4; ++m)
; #pragma unroll
;                     for (int n = 0; n < 2; ++n) acc[a][b][m][n] = (f32x4){0.f, 0.f, 0.f, 0.f};
;         cur = nxt; cA = nA; cB = nB; ++ui;
.LBB0_208:
	v_xor_b32_e32 v145, 64, v163
	v_xor_b32_e32 v147, 64, v188
	v_xor_b32_e32 v149, 64, v189
	v_xor_b32_e32 v151, 64, v161
	s_ashr_i32 s49, s48, 31
	s_lshl_b64 s[18:19], s[48:49], 20
	s_add_u32 s50, s12, s18
	s_addc_u32 s51, s13, s19
	s_and_b64 s[18:19], s[4:5], exec
	s_cselect_b32 s7, s51, s57
	s_cselect_b32 s18, s50, s56
	s_ashr_i32 s47, s46, 31
	s_lshl_b64 s[52:53], s[46:47], 20
	s_add_u32 s52, s8, s52
	s_addc_u32 s53, s9, s53
	s_and_b64 s[58:59], s[4:5], exec
	s_cselect_b32 s19, s53, s55
	s_cselect_b32 s20, s52, s54
	s_add_u32 s43, s54, 0x100
	s_addc_u32 s45, s55, 0
	s_add_u32 s54, s56, 0x80080
	v_mov_b32_e32 v0, 0
	s_addc_u32 s55, s57, 0
	s_mov_b32 s47, -2
	v_mov_b32_e32 v1, v0
	v_mov_b32_e32 v2, v0
	v_mov_b32_e32 v3, v0
	v_mov_b32_e32 v4, v0
	v_mov_b32_e32 v5, v0
	v_mov_b32_e32 v6, v0
	v_mov_b32_e32 v7, v0
	v_mov_b32_e32 v16, v0
	v_mov_b32_e32 v17, v0
	v_mov_b32_e32 v18, v0
	v_mov_b32_e32 v19, v0
	v_mov_b32_e32 v20, v0
	v_mov_b32_e32 v21, v0
	v_mov_b32_e32 v22, v0
	v_mov_b32_e32 v23, v0
	v_mov_b32_e32 v32, v0
	v_mov_b32_e32 v33, v0
	v_mov_b32_e32 v34, v0
	v_mov_b32_e32 v35, v0
	v_mov_b32_e32 v36, v0
	v_mov_b32_e32 v37, v0
	v_mov_b32_e32 v38, v0
	v_mov_b32_e32 v39, v0
	v_mov_b32_e32 v48, v0
	v_mov_b32_e32 v49, v0
	v_mov_b32_e32 v50, v0
	v_mov_b32_e32 v51, v0
	v_mov_b32_e32 v52, v0
	v_mov_b32_e32 v53, v0
	v_mov_b32_e32 v54, v0
	v_mov_b32_e32 v55, v0
	v_mov_b32_e32 v8, v0
	v_mov_b32_e32 v9, v0
	v_mov_b32_e32 v10, v0
	v_mov_b32_e32 v11, v0
	v_mov_b32_e32 v12, v0
	v_mov_b32_e32 v13, v0
	v_mov_b32_e32 v14, v0
	v_mov_b32_e32 v15, v0
	v_mov_b32_e32 v24, v0
	v_mov_b32_e32 v25, v0
	v_mov_b32_e32 v26, v0
	v_mov_b32_e32 v27, v0
	v_mov_b32_e32 v28, v0
	v_mov_b32_e32 v29, v0
	v_mov_b32_e32 v30, v0
	v_mov_b32_e32 v31, v0
	v_mov_b32_e32 v40, v0
	v_mov_b32_e32 v41, v0
	v_mov_b32_e32 v42, v0
	v_mov_b32_e32 v43, v0
	v_mov_b32_e32 v44, v0
	v_mov_b32_e32 v45, v0
	v_mov_b32_e32 v46, v0
	v_mov_b32_e32 v47, v0
	v_mov_b32_e32 v56, v0
	v_mov_b32_e32 v57, v0
	v_mov_b32_e32 v58, v0
	v_mov_b32_e32 v59, v0
	v_mov_b32_e32 v60, v0
	v_mov_b32_e32 v61, v0
	v_mov_b32_e32 v62, v0
	v_mov_b32_e32 v63, v0
	v_mov_b32_e32 v64, v0
	v_mov_b32_e32 v65, v0
	v_mov_b32_e32 v66, v0
	v_mov_b32_e32 v67, v0
	v_mov_b32_e32 v68, v0
	v_mov_b32_e32 v69, v0
	v_mov_b32_e32 v70, v0
	v_mov_b32_e32 v71, v0
	v_mov_b32_e32 v80, v0
	v_mov_b32_e32 v81, v0
	v_mov_b32_e32 v82, v0
	v_mov_b32_e32 v83, v0
	v_mov_b32_e32 v84, v0
	v_mov_b32_e32 v85, v0
	v_mov_b32_e32 v86, v0
	v_mov_b32_e32 v87, v0
	v_mov_b32_e32 v96, v0
	v_mov_b32_e32 v97, v0
	v_mov_b32_e32 v98, v0
	v_mov_b32_e32 v99, v0
	v_mov_b32_e32 v100, v0
	v_mov_b32_e32 v101, v0
	v_mov_b32_e32 v102, v0
	v_mov_b32_e32 v103, v0
	v_mov_b32_e32 v112, v0
	v_mov_b32_e32 v113, v0
	v_mov_b32_e32 v114, v0
	v_mov_b32_e32 v115, v0
	v_mov_b32_e32 v116, v0
	v_mov_b32_e32 v117, v0
	v_mov_b32_e32 v118, v0
	v_mov_b32_e32 v119, v0
	v_mov_b32_e32 v72, v0
	v_mov_b32_e32 v73, v0
	v_mov_b32_e32 v74, v0
	v_mov_b32_e32 v75, v0
	v_mov_b32_e32 v76, v0
	v_mov_b32_e32 v77, v0
	v_mov_b32_e32 v78, v0
	v_mov_b32_e32 v79, v0
	v_mov_b32_e32 v88, v0
	v_mov_b32_e32 v89, v0
	v_mov_b32_e32 v90, v0
	v_mov_b32_e32 v91, v0
	v_mov_b32_e32 v92, v0
	v_mov_b32_e32 v93, v0
	v_mov_b32_e32 v94, v0
	v_mov_b32_e32 v95, v0
	v_mov_b32_e32 v104, v0
	v_mov_b32_e32 v105, v0
	v_mov_b32_e32 v106, v0
	v_mov_b32_e32 v107, v0
	v_mov_b32_e32 v108, v0
	v_mov_b32_e32 v109, v0
	v_mov_b32_e32 v110, v0
	v_mov_b32_e32 v111, v0
	v_mov_b32_e32 v120, v0
	v_mov_b32_e32 v121, v0
	v_mov_b32_e32 v122, v0
	v_mov_b32_e32 v123, v0
	v_mov_b32_e32 v124, v0
	v_mov_b32_e32 v125, v0
	v_mov_b32_e32 v126, v0
	v_mov_b32_e32 v127, v0
.LBB0_209:
	ds_read_b128 v[174:177], v188
	ds_read_b128 v[178:181], v147
	ds_read_b128 v[190:193], v188 offset:2048
	ds_read_b128 v[194:197], v147 offset:2048
	ds_read_b128 v[198:201], v189
	ds_read_b128 v[202:205], v149
	ds_read_b128 v[206:209], v189 offset:2048
	ds_read_b128 v[210:213], v149 offset:2048
	s_add_u32 s49, s54, 0xfff80080
	s_addc_u32 s56, s55, -1
	s_cmp_eq_u32 s47, 28
	s_cselect_b32 s59, s7, s56
	s_cselect_b32 s58, s18, s49
	s_cselect_b32 s57, s19, s45
	s_cselect_b32 s56, s20, s43
	v_lshl_add_u64 v[182:183], s[54:55], 0, v[140:141]
	s_add_i32 m0, s1, 0xc000
	ds_read_b128 v[214:217], v163
	ds_read_b128 v[218:221], v145
	ds_read_b128 v[222:225], v163 offset:2048
	ds_read_b128 v[226:229], v145 offset:2048
	ds_read_b128 v[230:233], v163 offset:4096
	ds_read_b128 v[236:239], v145 offset:4096
	ds_read_b128 v[240:243], v163 offset:6144
	ds_read_b128 v[244:247], v145 offset:6144
	global_load_lds_dwordx4 v[182:183], off
	v_lshl_add_u64 v[182:183], s[54:55], 0, v[138:139]
	s_add_i32 m0, s1, 0xe000
	s_nop 0
	global_load_lds_dwordx4 v[182:183], off
	s_waitcnt vmcnt(8)
	s_waitcnt lgkmcnt(0)
	s_barrier
; #define PG8_STAGE(bufoff, gbase, voff) do { _Pragma("unroll") for (int _i = 0; _i < 2; ++_i) \
;         __builtin_amdgcn_global_load_lds((const unsigned*)((const char*)(gbase) + (voff)[_i]), (LAS unsigned*)(lds + (bufoff) + ldsw + _i * 8192), 16, 0, 0); } while (0)
; #define PG8_LDA(dst, b, h) do { _Pragma("unroll") for (int m = 0; m < 4; ++m) _Pragma("unroll") for (int k = 0; k < 2; ++k) dst[m][k] = *(const LAS bf16x8*)(lds + PG8_SA(b, h) + aoff + m * 2048 + k * 1024); } while (0)
; #define PG8_MMA(ai, bj, At, Bt) do { __builtin_amdgcn_s_setprio(1); _Pragma("unroll") for (int m = 0; m < 4; ++m) _Pragma("unroll") for (int n = 0; n < 2; ++n) _Pragma("unroll") for (int k = 0; k < 2; ++k) \
;         acc[ai][bj][m][n] = __builtin_amdgcn_mfma_f32_16x16x32_bf16(Bt[n][k], At[m][k], acc[ai][bj][m][n], 0, 0, 0); __builtin_amdgcn_s_setprio(0); } while (0)
; #define PG8_WAIT_V(n) asm volatile("s_waitcnt vmcnt(" #n ")" ::: "memory")
; #define PG8_WAIT_L(n) asm volatile("s_waitcnt lgkmcnt(" #n ")" ::: "memory")
; #define PG8_BAR __builtin_amdgcn_s_barrier()
; #define PG8_SCHED __builtin_amdgcn_sched_barrier(0)
; template <class Epi, class Sched>
; __device__ __forceinline__ void gemm_phase(LAS unsigned char* lds, const int K, const int lda, const int ldb, const Sched& S, const Epi& E) {
;     ...
;             PG8_WAIT_V(8); PG8_WAIT_L(0); PG8_BAR; PG8_MMA(0, 0, At, B0); PG8_MMA(0, 1, At, B1); PG8_BAR; PG8_SCHED;
;             PG8_LDA(At, 0, 1); PG8_STAGE(PG8_SB(0, 0), b2, voffB); PG8_STAGE(PG8_SB(0, 1), b2 + hB, voffB); PG8_STAGE(PG8_SA(0, 0), a2, voffA);
;             PG8_WAIT_V(8); PG8_WAIT_L(0); PG8_BAR; PG8_MMA(1, 0, At, B0); PG8_MMA(1, 1, At, B1); PG8_BAR; PG8_SCHED;
	s_setprio 1
	s_waitcnt lgkmcnt(0)
	v_mfma_f32_16x16x32_bf16 v[124:127], v[174:177], v[214:217], v[124:127]
	v_mfma_f32_16x16x32_bf16 v[120:123], v[190:193], v[214:217], v[120:123]
	v_mfma_f32_16x16x32_bf16 v[108:111], v[174:177], v[222:225], v[108:111]
	v_mfma_f32_16x16x32_bf16 v[104:107], v[190:193], v[222:225], v[104:107]
	v_mfma_f32_16x16x32_bf16 v[92:95], v[174:177], v[230:233], v[92:95]
	v_mfma_f32_16x16x32_bf16 v[88:91], v[190:193], v[230:233], v[88:91]
	v_mfma_f32_16x16x32_bf16 v[76:79], v[174:177], v[240:243], v[76:79]
	v_mfma_f32_16x16x32_bf16 v[72:75], v[190:193], v[240:243], v[72:75]
	v_mfma_f32_16x16x32_bf16 v[124:127], v[178:181], v[218:221], v[124:127]
	v_mfma_f32_16x16x32_bf16 v[120:123], v[194:197], v[218:221], v[120:123]
	v_mfma_f32_16x16x32_bf16 v[108:111], v[178:181], v[226:229], v[108:111]
	v_mfma_f32_16x16x32_bf16 v[104:107], v[194:197], v[226:229], v[104:107]
	v_mfma_f32_16x16x32_bf16 v[92:95], v[178:181], v[236:239], v[92:95]
	v_mfma_f32_16x16x32_bf16 v[88:91], v[194:197], v[236:239], v[88:91]
	v_mfma_f32_16x16x32_bf16 v[76:79], v[178:181], v[244:247], v[76:79]
	v_mfma_f32_16x16x32_bf16 v[72:75], v[194:197], v[244:247], v[72:75]
	s_setprio 0
	s_setprio 1
	v_mfma_f32_16x16x32_bf16 v[116:119], v[198:201], v[214:217], v[116:119]
	v_mfma_f32_16x16x32_bf16 v[112:115], v[206:209], v[214:217], v[112:115]
	v_mfma_f32_16x16x32_bf16 v[100:103], v[198:201], v[222:225], v[100:103]
	v_mfma_f32_16x16x32_bf16 v[96:99], v[206:209], v[222:225], v[96:99]
	v_mfma_f32_16x16x32_bf16 v[84:87], v[198:201], v[230:233], v[84:87]
	v_mfma_f32_16x16x32_bf16 v[80:83], v[206:209], v[230:233], v[80:83]
	v_mfma_f32_16x16x32_bf16 v[68:71], v[198:201], v[240:243], v[68:71]
	v_mfma_f32_16x16x32_bf16 v[64:67], v[206:209], v[240:243], v[64:67]
	v_mfma_f32_16x16x32_bf16 v[116:119], v[202:205], v[218:221], v[116:119]
	v_mfma_f32_16x16x32_bf16 v[112:115], v[210:213], v[218:221], v[112:115]
	v_mfma_f32_16x16x32_bf16 v[100:103], v[202:205], v[226:229], v[100:103]
	v_mfma_f32_16x16x32_bf16 v[96:99], v[210:213], v[226:229], v[96:99]
	v_mfma_f32_16x16x32_bf16 v[84:87], v[202:205], v[236:239], v[84:87]
	v_mfma_f32_16x16x32_bf16 v[80:83], v[210:213], v[236:239], v[80:83]
	v_mfma_f32_16x16x32_bf16 v[68:71], v[202:205], v[244:247], v[68:71]
	v_mfma_f32_16x16x32_bf16 v[64:67], v[210:213], v[244:247], v[64:67]
	s_setprio 0
	s_barrier
	s_add_i32 s49, s68, s2
	v_lshl_add_u64 v[182:183], s[56:57], 0, v[132:133]
	s_mov_b32 m0, s49
	ds_read_b128 v[214:217], v163 offset:16384
	ds_read_b128 v[218:221], v145 offset:16384
	ds_read_b128 v[222:225], v163 offset:18432
	ds_read_b128 v[226:229], v145 offset:18432
	ds_read_b128 v[230:233], v163 offset:20480
	ds_read_b128 v[236:239], v145 offset:20480
	ds_read_b128 v[240:243], v163 offset:22528
	ds_read_b128 v[244:247], v145 offset:22528
	global_load_lds_dwordx4 v[182:183], off
	s_add_i32 m0, s49, 0x2000
	s_add_u32 s60, s56, 0x80000
	v_lshl_add_u64 v[248:249], s[56:57], 0, v[128:129]
	s_addc_u32 s61, s57, 0
	s_add_i32 s49, s69, s2
	global_load_lds_dwordx4 v[248:249], off
	v_lshl_add_u64 v[250:251], s[60:61], 0, v[132:133]
	s_mov_b32 m0, s49
	v_lshl_add_u64 v[252:253], s[58:59], 0, v[130:131]
	global_load_lds_dwordx4 v[250:251], off
	v_lshl_add_u64 v[250:251], s[60:61], 0, v[128:129]
	s_add_i32 m0, s49, 0x2000
	s_nop 0
	global_load_lds_dwordx4 v[250:251], off
	v_lshl_add_u64 v[250:251], s[58:59], 0, v[134:135]
	s_mov_b32 m0, s1
	s_nop 0
	global_load_lds_dwordx4 v[250:251], off
	s_mov_b32 m0, s17
	s_nop 0
	global_load_lds_dwordx4 v[252:253], off
	s_waitcnt vmcnt(8)
	s_waitcnt lgkmcnt(0)
	s_barrier
	s_setprio 1
	s_waitcnt lgkmcnt(0)
	v_mfma_f32_16x16x32_bf16 v[60:63], v[174:177], v[214:217], v[60:63]
	v_mfma_f32_16x16x32_bf16 v[56:59], v[190:193], v[214:217], v[56:59]
	v_mfma_f32_16x16x32_bf16 v[44:47], v[174:177], v[222:225], v[44:47]
	v_mfma_f32_16x16x32_bf16 v[40:43], v[190:193], v[222:225], v[40:43]
	v_mfma_f32_16x16x32_bf16 v[28:31], v[174:177], v[230:233], v[28:31]
	v_mfma_f32_16x16x32_bf16 v[24:27], v[190:193], v[230:233], v[24:27]
	v_mfma_f32_16x16x32_bf16 v[12:15], v[174:177], v[240:243], v[12:15]
	v_mfma_f32_16x16x32_bf16 v[8:11], v[190:193], v[240:243], v[8:11]
	v_mfma_f32_16x16x32_bf16 v[60:63], v[178:181], v[218:221], v[60:63]
	v_mfma_f32_16x16x32_bf16 v[56:59], v[194:197], v[218:221], v[56:59]
	v_mfma_f32_16x16x32_bf16 v[44:47], v[178:181], v[226:229], v[44:47]
	v_mfma_f32_16x16x32_bf16 v[40:43], v[194:197], v[226:229], v[40:43]
	v_mfma_f32_16x16x32_bf16 v[28:31], v[178:181], v[236:239], v[28:31]
	v_mfma_f32_16x16x32_bf16 v[24:27], v[194:197], v[236:239], v[24:27]
	v_mfma_f32_16x16x32_bf16 v[12:15], v[178:181], v[244:247], v[12:15]
	v_mfma_f32_16x16x32_bf16 v[8:11], v[194:197], v[244:247], v[8:11]
	s_setprio 0
	s_setprio 1
	v_mfma_f32_16x16x32_bf16 v[52:55], v[198:201], v[214:217], v[52:55]
	v_mfma_f32_16x16x32_bf16 v[48:51], v[206:209], v[214:217], v[48:51]
	v_mfma_f32_16x16x32_bf16 v[36:39], v[198:201], v[222:225], v[36:39]
	v_mfma_f32_16x16x32_bf16 v[32:35], v[206:209], v[222:225], v[32:35]
	v_mfma_f32_16x16x32_bf16 v[20:23], v[198:201], v[230:233], v[20:23]
	v_mfma_f32_16x16x32_bf16 v[16:19], v[206:209], v[230:233], v[16:19]
	v_mfma_f32_16x16x32_bf16 v[4:7], v[198:201], v[240:243], v[4:7]
	v_mfma_f32_16x16x32_bf16 v[0:3], v[206:209], v[240:243], v[0:3]
	v_mfma_f32_16x16x32_bf16 v[52:55], v[202:205], v[218:221], v[52:55]
	v_mfma_f32_16x16x32_bf16 v[48:51], v[210:213], v[218:221], v[48:51]
	v_mfma_f32_16x16x32_bf16 v[36:39], v[202:205], v[226:229], v[36:39]
	v_mfma_f32_16x16x32_bf16 v[32:35], v[210:213], v[226:229], v[32:35]
	v_mfma_f32_16x16x32_bf16 v[20:23], v[202:205], v[236:239], v[20:23]
	v_mfma_f32_16x16x32_bf16 v[16:19], v[210:213], v[236:239], v[16:19]
	v_mfma_f32_16x16x32_bf16 v[4:7], v[202:205], v[244:247], v[4:7]
	v_mfma_f32_16x16x32_bf16 v[0:3], v[210:213], v[244:247], v[0:3]
	s_setprio 0
	s_barrier
; #define PG8_STAGE(bufoff, gbase, voff) do { _Pragma("unroll") for (int _i = 0; _i < 2; ++_i) \
;         __builtin_amdgcn_global_load_lds((const unsigned*)((const char*)(gbase) + (voff)[_i]), (LAS unsigned*)(lds + (bufoff) + ldsw + _i * 8192), 16, 0, 0); } while (0)
; #define PG8_LDA(dst, b, h) do { _Pragma("unroll") for (int m = 0; m < 4; ++m) _Pragma("unroll") for (int k = 0; k < 2; ++k) dst[m][k] = *(const LAS bf16x8*)(lds + PG8_SA(b, h) + aoff + m * 2048 + k * 1024); } while (0)
; #define PG8_LDB(dst, b, h) do { _Pragma("unroll") for (int n = 0; n < 2; ++n) _Pragma("unroll") for (int k = 0; k < 2; ++k) dst[n][k] = *(const LAS bf16x8*)(lds + PG8_SB(b, h) + boff + n * 2048 + k * 1024); } while (0)
; #define PG8_MMA(ai, bj, At, Bt) do { __builtin_amdgcn_s_setprio(1); _Pragma("unroll") for (int m = 0; m < 4; ++m) _Pragma("unroll") for (int n = 0; n < 2; ++n) _Pragma("unroll") for (int k = 0; k < 2; ++k) \
;         acc[ai][bj][m][n] = __builtin_amdgcn_mfma_f32_16x16x32_bf16(Bt[n][k], At[m][k], acc[ai][bj][m][n], 0, 0, 0); __builtin_amdgcn_s_setprio(0); } while (0)
; #define PG8_WAIT_V(n) asm volatile("s_waitcnt vmcnt(" #n ")" ::: "memory")
; #define PG8_WAIT_L(n) asm volatile("s_waitcnt lgkmcnt(" #n ")" ::: "memory")
; #define PG8_BAR __builtin_amdgcn_s_barrier()
; #define PG8_SCHED __builtin_amdgcn_sched_barrier(0)
; template <class Epi, class Sched>
; __device__ __forceinline__ void gemm_phase(LAS unsigned char* lds, const int K, const int lda, const int ldb, const Sched& S, const Epi& E) {
;     ...
;             PG8_LDB(B0, 1, 0); PG8_LDB(B1, 1, 1); PG8_SCHED; PG8_LDA(At, 1, 0); PG8_STAGE(PG8_SA(0, 1), a2 + hA, voffA);
;             PG8_WAIT_V(8); PG8_WAIT_L(0); PG8_BAR; PG8_MMA(0, 0, At, B0); PG8_MMA(0, 1, At, B1); PG8_BAR; PG8_SCHED;
	s_add_i32 s49, 0, 0x18000
	v_add_u32_e32 v143, s49, v161
	v_add_u32_e32 v158, s49, v151
	s_add_i32 s60, 0, 0x1c000
	ds_read_b128 v[174:177], v143
	ds_read_b128 v[178:181], v158
	ds_read_b128 v[190:193], v143 offset:2048
	ds_read_b128 v[194:197], v158 offset:2048
	v_add_u32_e32 v143, 0x19000, v161
	v_add_u32_e32 v158, 0x19000, v151
	ds_read_b128 v[198:201], v143
	ds_read_b128 v[202:205], v158
	ds_read_b128 v[206:209], v143 offset:2048
	ds_read_b128 v[210:213], v158 offset:2048
	s_add_u32 s58, s58, 0x80000
	s_addc_u32 s59, s59, 0
	s_mov_b32 m0, s29
	v_lshl_add_u64 v[234:235], s[58:59], 0, v[134:135]
	ds_read_b128 v[214:217], v163 offset:32768
	ds_read_b128 v[218:221], v145 offset:32768
	ds_read_b128 v[222:225], v163 offset:34816
	ds_read_b128 v[226:229], v145 offset:34816
	ds_read_b128 v[230:233], v163 offset:36864
	ds_read_b128 v[236:239], v145 offset:36864
	ds_read_b128 v[240:243], v163 offset:38912
	ds_read_b128 v[244:247], v145 offset:38912
	global_load_lds_dwordx4 v[234:235], off
	v_lshl_add_u64 v[234:235], s[58:59], 0, v[130:131]
	s_mov_b32 m0, s34
	s_nop 0
	global_load_lds_dwordx4 v[234:235], off
	s_waitcnt vmcnt(8)
	s_waitcnt lgkmcnt(0)
	s_barrier
	s_setprio 1
	s_waitcnt lgkmcnt(0)
	v_mfma_f32_16x16x32_bf16 v[124:127], v[174:177], v[214:217], v[124:127]
	v_mfma_f32_16x16x32_bf16 v[120:123], v[190:193], v[214:217], v[120:123]
	v_mfma_f32_16x16x32_bf16 v[108:111], v[174:177], v[222:225], v[108:111]
	v_mfma_f32_16x16x32_bf16 v[104:107], v[190:193], v[222:225], v[104:107]
	v_mfma_f32_16x16x32_bf16 v[92:95], v[174:177], v[230:233], v[92:95]
	v_mfma_f32_16x16x32_bf16 v[88:91], v[190:193], v[230:233], v[88:91]
	v_mfma_f32_16x16x32_bf16 v[76:79], v[174:177], v[240:243], v[76:79]
	v_mfma_f32_16x16x32_bf16 v[72:75], v[190:193], v[240:243], v[72:75]
	v_mfma_f32_16x16x32_bf16 v[124:127], v[178:181], v[218:221], v[124:127]
	v_mfma_f32_16x16x32_bf16 v[120:123], v[194:197], v[218:221], v[120:123]
	v_mfma_f32_16x16x32_bf16 v[108:111], v[178:181], v[226:229], v[108:111]
	v_mfma_f32_16x16x32_bf16 v[104:107], v[194:197], v[226:229], v[104:107]
	v_mfma_f32_16x16x32_bf16 v[92:95], v[178:181], v[236:239], v[92:95]
	v_mfma_f32_16x16x32_bf16 v[88:91], v[194:197], v[236:239], v[88:91]
	v_mfma_f32_16x16x32_bf16 v[76:79], v[178:181], v[244:247], v[76:79]
	v_mfma_f32_16x16x32_bf16 v[72:75], v[194:197], v[244:247], v[72:75]
	s_setprio 0
	s_setprio 1
	v_mfma_f32_16x16x32_bf16 v[116:119], v[198:201], v[214:217], v[116:119]
	v_mfma_f32_16x16x32_bf16 v[112:115], v[206:209], v[214:217], v[112:115]
	v_mfma_f32_16x16x32_bf16 v[100:103], v[198:201], v[222:225], v[100:103]
	v_mfma_f32_16x16x32_bf16 v[96:99], v[206:209], v[222:225], v[96:99]
	v_mfma_f32_16x16x32_bf16 v[84:87], v[198:201], v[230:233], v[84:87]
	v_mfma_f32_16x16x32_bf16 v[80:83], v[206:209], v[230:233], v[80:83]
	v_mfma_f32_16x16x32_bf16 v[68:71], v[198:201], v[240:243], v[68:71]
	v_mfma_f32_16x16x32_bf16 v[64:67], v[206:209], v[240:243], v[64:67]
	v_mfma_f32_16x16x32_bf16 v[116:119], v[202:205], v[218:221], v[116:119]
	v_mfma_f32_16x16x32_bf16 v[112:115], v[210:213], v[218:221], v[112:115]
	v_mfma_f32_16x16x32_bf16 v[100:103], v[202:205], v[226:229], v[100:103]
	v_mfma_f32_16x16x32_bf16 v[96:99], v[210:213], v[226:229], v[96:99]
	v_mfma_f32_16x16x32_bf16 v[84:87], v[202:205], v[236:239], v[84:87]
	v_mfma_f32_16x16x32_bf16 v[80:83], v[210:213], v[236:239], v[80:83]
	v_mfma_f32_16x16x32_bf16 v[68:71], v[202:205], v[244:247], v[68:71]
	v_mfma_f32_16x16x32_bf16 v[64:67], v[210:213], v[244:247], v[64:67]
	s_setprio 0
	s_barrier
; #define PG8_STAGE(bufoff, gbase, voff) do { _Pragma("unroll") for (int _i = 0; _i < 2; ++_i) \
;         __builtin_amdgcn_global_load_lds((const unsigned*)((const char*)(gbase) + (voff)[_i]), (LAS unsigned*)(lds + (bufoff) + ldsw + _i * 8192), 16, 0, 0); } while (0)
; #define PG8_LDA(dst, b, h) do { _Pragma("unroll") for (int m = 0; m < 4; ++m) _Pragma("unroll") for (int k = 0; k < 2; ++k) dst[m][k] = *(const LAS bf16x8*)(lds + PG8_SA(b, h) + aoff + m * 2048 + k * 1024); } while (0)
; #define PG8_MMA(ai, bj, At, Bt) do { __builtin_amdgcn_s_setprio(1); _Pragma("unroll") for (int m = 0; m < 4; ++m) _Pragma("unroll") for (int n = 0; n < 2; ++n) _Pragma("unroll") for (int k = 0; k < 2; ++k) \
;         acc[ai][bj][m][n] = __builtin_amdgcn_mfma_f32_16x16x32_bf16(Bt[n][k], At[m][k], acc[ai][bj][m][n], 0, 0, 0); __builtin_amdgcn_s_setprio(0); } while (0)
; #define PG8_WAIT_V(n) asm volatile("s_waitcnt vmcnt(" #n ")" ::: "memory")
; #define PG8_WAIT_L(n) asm volatile("s_waitcnt lgkmcnt(" #n ")" ::: "memory")
; #define PG8_BAR __builtin_amdgcn_s_barrier()
; #define PG8_SCHED __builtin_amdgcn_sched_barrier(0)
; template <class Epi, class Sched>
; __device__ __forceinline__ void gemm_phase(LAS unsigned char* lds, const int K, const int lda, const int ldb, const Sched& S, const Epi& E) {
;     ...
;             PG8_LDA(At, 1, 1); PG8_STAGE(PG8_SB(1, 0), b3, voffB); PG8_STAGE(PG8_SB(1, 1), b3 + hB, voffB); PG8_STAGE(PG8_SA(1, 0), a3, voffA);
;             PG8_WAIT_V(8); PG8_WAIT_L(0); PG8_BAR; PG8_MMA(1, 0, At, B0); PG8_MMA(1, 1, At, B1); PG8_BAR; PG8_SCHED;
;         }
	s_add_i32 s49, s49, s2
	v_lshl_add_u64 v[182:183], v[182:183], 0, s[22:23]
	s_mov_b32 m0, s49
	ds_read_b128 v[214:217], v163 offset:49152
	ds_read_b128 v[218:221], v145 offset:49152
	ds_read_b128 v[222:225], v163 offset:51200
	ds_read_b128 v[226:229], v145 offset:51200
	ds_read_b128 v[230:233], v163 offset:53248
	ds_read_b128 v[236:239], v145 offset:53248
	ds_read_b128 v[240:243], v163 offset:55296
	ds_read_b128 v[244:247], v145 offset:55296
	global_load_lds_dwordx4 v[182:183], off
	s_add_i32 m0, s49, 0x2000
	s_add_u32 s56, s56, 0x80080
	v_lshl_add_u64 v[182:183], v[248:249], 0, s[22:23]
	s_addc_u32 s57, s57, 0
	s_add_i32 s49, s60, s2
	global_load_lds_dwordx4 v[182:183], off
	v_lshl_add_u64 v[182:183], s[56:57], 0, v[132:133]
	s_mov_b32 m0, s49
	s_nop 0
	global_load_lds_dwordx4 v[182:183], off
	v_lshl_add_u64 v[182:183], s[56:57], 0, v[128:129]
	s_add_i32 m0, s49, 0x2000
	s_nop 0
	global_load_lds_dwordx4 v[182:183], off
	v_lshl_add_u64 v[182:183], v[250:251], 0, s[22:23]
	s_mov_b32 m0, s38
	s_nop 0
	global_load_lds_dwordx4 v[182:183], off
	v_lshl_add_u64 v[182:183], v[252:253], 0, s[22:23]
	s_mov_b32 m0, s39
	s_nop 0
	global_load_lds_dwordx4 v[182:183], off
	s_waitcnt vmcnt(8)
	s_waitcnt lgkmcnt(0)
	s_barrier
	s_setprio 1
	s_waitcnt lgkmcnt(0)
	v_mfma_f32_16x16x32_bf16 v[60:63], v[174:177], v[214:217], v[60:63]
	v_mfma_f32_16x16x32_bf16 v[56:59], v[190:193], v[214:217], v[56:59]
	v_mfma_f32_16x16x32_bf16 v[44:47], v[174:177], v[222:225], v[44:47]
	v_mfma_f32_16x16x32_bf16 v[40:43], v[190:193], v[222:225], v[40:43]
	v_mfma_f32_16x16x32_bf16 v[28:31], v[174:177], v[230:233], v[28:31]
	v_mfma_f32_16x16x32_bf16 v[24:27], v[190:193], v[230:233], v[24:27]
	v_mfma_f32_16x16x32_bf16 v[12:15], v[174:177], v[240:243], v[12:15]
	v_mfma_f32_16x16x32_bf16 v[8:11], v[190:193], v[240:243], v[8:11]
	v_mfma_f32_16x16x32_bf16 v[60:63], v[178:181], v[218:221], v[60:63]
	v_mfma_f32_16x16x32_bf16 v[56:59], v[194:197], v[218:221], v[56:59]
	v_mfma_f32_16x16x32_bf16 v[44:47], v[178:181], v[226:229], v[44:47]
	v_mfma_f32_16x16x32_bf16 v[40:43], v[194:197], v[226:229], v[40:43]
	v_mfma_f32_16x16x32_bf16 v[28:31], v[178:181], v[236:239], v[28:31]
	v_mfma_f32_16x16x32_bf16 v[24:27], v[194:197], v[236:239], v[24:27]
	v_mfma_f32_16x16x32_bf16 v[12:15], v[178:181], v[244:247], v[12:15]
	v_mfma_f32_16x16x32_bf16 v[8:11], v[194:197], v[244:247], v[8:11]
	s_setprio 0
	s_setprio 1
	v_mfma_f32_16x16x32_bf16 v[52:55], v[198:201], v[214:217], v[52:55]
	v_mfma_f32_16x16x32_bf16 v[48:51], v[206:209], v[214:217], v[48:51]
	v_mfma_f32_16x16x32_bf16 v[36:39], v[198:201], v[222:225], v[36:39]
	v_mfma_f32_16x16x32_bf16 v[32:35], v[206:209], v[222:225], v[32:35]
	v_mfma_f32_16x16x32_bf16 v[20:23], v[198:201], v[230:233], v[20:23]
	v_mfma_f32_16x16x32_bf16 v[16:19], v[206:209], v[230:233], v[16:19]
	v_mfma_f32_16x16x32_bf16 v[4:7], v[198:201], v[240:243], v[4:7]
	v_mfma_f32_16x16x32_bf16 v[0:3], v[206:209], v[240:243], v[0:3]
	v_mfma_f32_16x16x32_bf16 v[52:55], v[202:205], v[218:221], v[52:55]
	v_mfma_f32_16x16x32_bf16 v[48:51], v[210:213], v[218:221], v[48:51]
	v_mfma_f32_16x16x32_bf16 v[36:39], v[202:205], v[226:229], v[36:39]
	v_mfma_f32_16x16x32_bf16 v[32:35], v[210:213], v[226:229], v[32:35]
	v_mfma_f32_16x16x32_bf16 v[20:23], v[202:205], v[236:239], v[20:23]
	v_mfma_f32_16x16x32_bf16 v[16:19], v[210:213], v[236:239], v[16:19]
	v_mfma_f32_16x16x32_bf16 v[4:7], v[202:205], v[244:247], v[4:7]
	v_mfma_f32_16x16x32_bf16 v[0:3], v[210:213], v[244:247], v[0:3]
	s_setprio 0
	s_barrier
	s_add_i32 s47, s47, 2
	s_add_u32 s43, s43, 0x100
	s_addc_u32 s45, s45, 0
	s_add_u32 s54, s54, 0x100
	s_addc_u32 s55, s55, 0
	s_cmp_gt_u32 s47, 29
	s_cbranch_scc0 .LBB0_209
	s_and_b64 vcc, exec, s[24:25]
	s_cbranch_vccz .LBB0_212
	s_barrier

; #define PG8_STAGE(bufoff, gbase, voff) do { _Pragma("unroll") for (int _i = 0; _i < 2; ++_i) \
;         __builtin_amdgcn_global_load_lds((const unsigned*)((const char*)(gbase) + (voff)[_i]), (LAS unsigned*)(lds + (bufoff) + ldsw + _i * 8192), 16, 0, 0); } while (0)
; #define PG8_WAIT_V(n) asm volatile("s_waitcnt vmcnt(" #n ")" ::: "memory")
; #define PG8_BAR __builtin_amdgcn_s_barrier()
; template <class Epi, class Sched>
; __device__ __forceinline__ void gemm_phase(LAS unsigned char* lds, const int K, const int lda, const int ldb, const Sched& S, const Epi& E) {
;     ...
;     for (int i = 0; i < 2; ++i) { int R, C; stage_rc(tid * 16 + i * 8192, R, C); const int Rb = (R & ~31) + perm32(R & 31);
;         voffA[i] = (unsigned)(R * lda + C) * 2u; voffB[i] = (unsigned)(Rb * ldb + C) * 2u; }
;     const size_t kstep = (size_t)(BK * 2);
;     const size_t hA = (size_t)HALF * lda * 2, hB = (size_t)HALF * ldb * 2;
;     const unsigned ldsw = (unsigned)wid * 1024u;
;     const int aoff = lds_byte(wr * 64 + fr, fq * 8), boff = lds_byte(wc * 32 + fr, fq * 8);
;     ...
;     const char* cA = S.aptr(cur); const char* cB = S.bptr(cur);
;     PG8_STAGE(PG8_SB(0, 0), cB, voffB); PG8_STAGE(PG8_SB(0, 1), cB + hB, voffB); PG8_STAGE(PG8_SA(0, 0), cA, voffA); PG8_STAGE(PG8_SA(0, 1), cA + hA, voffA);
;     if (wr == 1) PG8_BAR;
;     PG8_WAIT_V(2); PG8_BAR;
.LBB0_954:
	s_or_b64 exec, exec, s[8:9]
	s_add_u32 s42, s48, 0x2e00000
	s_addc_u32 s43, s49, 0
	s_add_u32 s44, s48, 0x200000
	s_addc_u32 s45, s49, 0
	v_readlane_b32 s0, v255, 3
	s_add_u32 s12, s48, 0xa00000
	v_mov_b32_e32 v10, v254
	v_readlane_b32 s1, v255, 4
	s_addc_u32 s13, s49, 0
	s_barrier
	s_andn2_b64 vcc, exec, s[0:1]
	v_readfirstlane_b32 s9, v10
	s_cbranch_vccnz .LBB0_989
	v_lshlrev_b32_e32 v0, 4, v10
	v_add_u32_e32 v1, 0x2000, v0
	v_ashrrev_i32_e32 v2, 31, v1
	v_lshrrev_b32_e32 v2, 22, v2
	v_add_u32_e32 v2, v1, v2
	v_ashrrev_i32_e32 v8, 10, v2
	v_mul_i32_i24_e32 v2, 0x400, v8
	v_sub_u32_e32 v1, v1, v2
	v_lshrrev_b32_e32 v2, 4, v1
	v_bitop3_b32 v1, v2, v1, 32 bitop3:0x6c
	v_ashrrev_i32_e32 v2, 31, v1
	v_lshrrev_b32_e32 v2, 26, v2
	v_add_u32_e32 v2, v1, v2
	v_lshlrev_b32_e32 v3, 3, v8
	v_ashrrev_i32_e32 v9, 6, v2
	v_and_b32_e32 v3, -16, v3
	v_add_u32_e32 v3, v9, v3
	v_and_b32_e32 v4, 3, v9
	s_mov_b32 s0, 0xfffe0
	v_lshrrev_b32_e32 v5, 2, v3
	v_lshlrev_b32_e32 v6, 1, v3
	v_and_b32_e32 v2, 0xc0, v2
	v_and_or_b32 v4, v3, s0, v4
	v_and_b32_e32 v5, 4, v5
	v_and_b32_e32 v6, 24, v6
	v_sub_u32_e32 v1, v1, v2
	v_mov_b32_e32 v2, 1
	v_or3_b32 v4, v4, v5, v6
	v_lshlrev_b32_e32 v5, 5, v8
	v_ashrrev_i16_sdwa v1, v2, sext(v1) dst_sel:DWORD dst_unused:UNUSED_PAD src0_sel:DWORD src1_sel:BYTE_0
	v_and_b32_e32 v5, 32, v5
	v_bfe_i32 v11, v1, 0, 16
	v_add_lshl_u32 v1, v5, v11, 1
	v_and_b32_e32 v242, 63, v254
	v_lshrrev_b32_e32 v243, 6, v254
	v_lshrrev_b32_e32 v244, 3, v242
	v_lshl_add_u32 v245, v243, 3, v244
	v_and_b32_e32 v246, 1, v243
	v_bfe_u32 v247, v242, 4, 2
	v_lshl_add_u32 v247, v246, 2, v247
	v_and_b32_e32 v237, 7, v242
	v_xor_b32_e32 v247, v237, v247
	v_lshlrev_b32_e32 v247, 4, v247
	v_lshl_add_u32 v236, v245, 12, v247
	v_add_u32_e32 v237, 0x40000, v236
	v_lshrrev_b32_e32 v245, 5, v242
	v_lshlrev_b32_e32 v245, 3, v245
	v_lshl_add_u32 v245, v246, 4, v245
	v_bfe_u32 v246, v243, 1, 1
	v_lshl_add_u32 v245, v246, 2, v245
	v_and_b32_e32 v246, 3, v244
	v_add_u32_e32 v245, v245, v246
	v_lshrrev_b32_e32 v246, 2, v243
	v_lshl_add_u32 v245, v246, 5, v245
	v_lshl_add_u32 v238, v245, 12, v247
	v_add_u32_e32 v239, 0x40000, v238
	v_and_b32_e32 v242, 15, v254
	v_bfe_u32 v244, v254, 4, 2
	v_bfe_u32 v245, v254, 1, 3
	v_xor_b32_e32 v244, v244, v245
	v_lshlrev_b32_e32 v244, 4, v244
	v_lshl_add_u32 v244, v242, 7, v244
	v_lshrrev_b32_e32 v245, 8, v254
	v_lshl_add_u32 v240, v245, 13, v244
	v_and_b32_e32 v245, 3, v243
	v_lshl_add_u32 v241, v245, 13, v244
	v_mov_b32_e32 v128, v239
	v_mov_b32_e32 v130, v237
	v_bfe_i32 v1, v10, 27, 1
	v_lshrrev_b32_e32 v1, 22, v1
	v_add_u32_e32 v1, v0, v1
	v_and_b32_e32 v1, 0xfffffc00, v1
	v_sub_u32_e32 v0, v0, v1
	v_lshrrev_b32_e32 v1, 4, v0
	v_ashrrev_i32_e32 v3, 31, v10
	v_bitop3_b32 v0, v1, v0, 32 bitop3:0x6c
	v_lshrrev_b32_e32 v3, 26, v3
	v_ashrrev_i32_e32 v1, 31, v0
	v_add_u32_e32 v3, v10, v3
	v_lshrrev_b32_e32 v1, 26, v1
	v_ashrrev_i32_e32 v13, 6, v3
	v_add_u32_e32 v1, v0, v1
	v_lshlrev_b32_e32 v3, 3, v13
	v_ashrrev_i32_e32 v12, 6, v1
	v_and_b32_e32 v3, -16, v3
	v_add_u32_e32 v3, v12, v3
	v_and_b32_e32 v4, 3, v12
	s_ashr_i32 s4, s33, 31
	v_and_or_b32 v4, v3, s0, v4
	s_lshr_b32 s0, s4, 29
	s_add_i32 s0, s33, s0
	s_ashr_i32 s18, s9, 6
	s_ashr_i32 s1, s0, 3
	s_and_b32 s0, s0, -8
	s_ashr_i32 s17, s9, 8
	s_lshl_b32 s2, s18, 10
	s_sub_i32 s0, s33, s0
	s_cmp_lt_i32 s0, 0
	s_movk_i32 s5, 0x141
	s_cselect_b32 s6, s5, 0x140
	s_mul_i32 s0, s6, s0
	s_add_i32 s0, s0, s1
	s_mul_hi_i32 s1, s0, 0x66666667
	s_lshr_b32 s6, s1, 31
	s_ashr_i32 s1, s1, 6
	s_add_i32 s1, s1, s6
	s_lshl_b32 s6, s1, 3
	s_mulk_i32 s1, 0xa0
	s_sub_i32 s0, s0, s1
	s_sext_i32_i16 s1, s0
	s_bfe_u32 s1, s1, 0x3001c
	s_add_i32 s1, s0, s1
	s_sext_i32_i16 s7, s1
	s_and_b32 s1, s1, 0xfff8
	s_sub_i32 s0, s0, s1
	s_sext_i32_i16 s0, s0
	v_lshrrev_b32_e32 v5, 2, v3
	v_lshlrev_b32_e32 v6, 1, v3
	v_and_b32_e32 v1, 0xc0, v1
	s_lshr_b32 s8, s7, 3
	s_add_i32 s10, s6, s0
	v_and_b32_e32 v5, 4, v5
	v_and_b32_e32 v6, 24, v6
	v_sub_u32_e32 v0, v0, v1
	s_ashr_i32 s11, s10, 31
	s_bfe_i64 s[0:1], s[8:9], 0x100000
	v_or3_b32 v4, v4, v5, v6
	v_lshlrev_b32_e32 v5, 5, v13
	v_ashrrev_i16_sdwa v0, v2, sext(v0) dst_sel:DWORD dst_unused:UNUSED_PAD src0_sel:DWORD src1_sel:BYTE_0
	s_lshl_b64 s[6:7], s[10:11], 20
	s_lshl_b64 s[0:1], s[0:1], 20
	v_and_b32_e32 v5, 32, v5
	v_bfe_i32 v14, v0, 0, 16
	s_add_u32 s66, s12, s0
	v_add_lshl_u32 v0, v5, v14, 1
	s_addc_u32 s67, s13, s1
	s_add_i32 s1, s2, 0
	v_mov_b32_e32 v132, v238
	s_add_i32 m0, s1, 0x10000
	v_mov_b32_e32 v134, v236
	global_load_lds_dwordx4 v132, s[66:67]
	s_add_i32 m0, s1, 0x12000
	s_add_u32 s14, s66, 0x80000
	global_load_lds_dwordx4 v128, s[66:67]
	s_addc_u32 s15, s67, 0
	s_add_i32 m0, s1, 0x14000
	v_mov_b32_e32 v137, 0
	global_load_lds_dwordx4 v132, s[14:15]
	s_add_i32 m0, s1, 0x16000
	s_add_u32 s68, s42, s6
	s_addc_u32 s69, s43, s7
	s_add_i32 s6, s1, 0x2000
	global_load_lds_dwordx4 v128, s[14:15]
	s_mov_b32 m0, s1
	s_add_u32 s24, s68, 0x80000
	global_load_lds_dwordx4 v134, s[68:69]
	s_mov_b32 m0, s6
	s_addc_u32 s25, s69, 0
	s_add_i32 s7, s1, 0x4000
	global_load_lds_dwordx4 v130, s[68:69]
	s_mov_b32 m0, s7
	s_add_i32 s14, s1, 0x6000
	global_load_lds_dwordx4 v134, s[24:25]
	s_mov_b32 m0, s14
	v_mov_b32_e32 v133, v137
	global_load_lds_dwordx4 v130, s[24:25]
	v_mov_b32_e32 v129, v137
	v_mov_b32_e32 v135, v137
	v_mov_b32_e32 v131, v137
	s_cmp_eq_u32 s17, 1
	s_mov_b32 s19, 0
	v_lshl_add_u64 v[6:7], s[66:67], 0, v[132:133]
	v_lshl_add_u64 v[4:5], s[66:67], 0, v[128:129]
	v_lshl_add_u64 v[0:1], s[68:69], 0, v[134:135]
	s_cselect_b64 s[46:47], -1, 0
	s_cmp_lg_u32 s17, 1
	v_lshl_add_u64 v[2:3], s[68:69], 0, v[130:131]
	s_cbranch_scc1 .LBB0_957
	s_barrier
; #define PG8_STAGE(bufoff, gbase, voff) do { _Pragma("unroll") for (int _i = 0; _i < 2; ++_i) \
;         __builtin_amdgcn_global_load_lds((const unsigned*)((const char*)(gbase) + (voff)[_i]), (LAS unsigned*)(lds + (bufoff) + ldsw + _i * 8192), 16, 0, 0); } while (0)
; #define PG8_WAIT_V(n) asm volatile("s_waitcnt vmcnt(" #n ")" ::: "memory")
; #define PG8_BAR __builtin_amdgcn_s_barrier()
; template <class Epi, class Sched>
; __device__ __forceinline__ void gemm_phase(LAS unsigned char* lds, const int K, const int lda, const int ldb, const Sched& S, const Epi& E) {
;     ...
;     const unsigned ldsw = (unsigned)wid * 1024u;
;     const int aoff = lds_byte(wr * 64 + fr, fq * 8), boff = lds_byte(wc * 32 + fr, fq * 8);
;     ...
;     PG8_STAGE(PG8_SB(1, 0), cB + kstep, voffB); PG8_STAGE(PG8_SA(1, 0), cA + kstep, voffA); PG8_STAGE(PG8_SB(1, 1), cB + hB + kstep, voffB);
;     PG8_WAIT_V(6); PG8_BAR;
.LBB0_957:
	s_sext_i32_i16 s0, s8
	v_and_b32_e32 v157, 15, v10
	s_and_b32 s8, s18, 3
	v_and_b32_e32 v17, 48, v10
	v_lshlrev_b32_e32 v18, 2, v10
	s_mov_b64 s[50:51], 0x80
	s_lshl_b32 s15, s17, 6
	s_lshl_b32 s11, s17, 13
	v_lshl_or_b32 v17, v157, 6, v17
	v_and_b32_e32 v18, 32, v18
	s_lshl_b32 s17, s8, 12
	s_add_i32 m0, s1, 0x18000
	v_lshl_add_u64 v[6:7], v[6:7], 0, s[50:51]
	v_bitop3_b32 v19, v17, s11, v18 bitop3:0xde
	s_lshl_b32 s11, s8, 5
	v_mov_b32_e32 v161, v241
	s_waitcnt vmcnt(2)
	s_barrier
	global_load_lds_dwordx4 v[6:7], off
	v_lshl_add_u64 v[4:5], v[4:5], 0, s[50:51]
	s_add_i32 m0, s1, 0x1a000
	s_add_i32 s17, s1, 0x8000
	s_add_i32 s21, s1, 0xa000
	global_load_lds_dwordx4 v[4:5], off
	v_lshl_add_u64 v[0:1], v[0:1], 0, s[50:51]
	s_mov_b32 m0, s17
	s_add_u32 s24, s66, 0x80080
	global_load_lds_dwordx4 v[0:1], off
	v_lshl_add_u64 v[0:1], v[2:3], 0, s[50:51]
	s_mov_b32 m0, s21
	s_addc_u32 s25, s67, 0
	global_load_lds_dwordx4 v[0:1], off
	s_add_i32 m0, s1, 0x1c000
	v_lshl_add_u64 v[0:1], s[24:25], 0, v[132:133]
	global_load_lds_dwordx4 v[0:1], off
	v_lshl_add_u64 v[0:1], s[24:25], 0, v[128:129]
	s_add_i32 m0, s1, 0x1e000
	s_cmpk_lt_u32 s9, 0x100
	global_load_lds_dwordx4 v[0:1], off
	v_lshlrev_b32_e32 v26, 15, v8
	s_cselect_b64 s[52:53], -1, 0
	s_lshl_b32 s9, s18, 12
	v_and_b32_e32 v26, 0xffff0000, v26
	s_add_i32 s9, s9, 0
	v_lshl_add_u32 v9, v9, 12, v26
	v_and_b32_e32 v8, 1, v8
	s_add_i32 s9, s9, 0x20000
	v_lshl_or_b32 v8, v8, 6, v9
	s_add_u32 s23, s48, 0x1ce00000
	v_lshlrev_b32_e32 v0, 1, v10
	v_mov_b32_e32 v138, v237
	v_lshlrev_b32_e32 v8, 15, v13
	v_bfe_u32 v15, v10, 4, 2
	s_addc_u32 s24, s49, 0
	v_and_b32_e32 v0, 14, v0
	v_bfe_u32 v2, v10, 3, 1
	v_and_b32_e32 v8, 0xffff0000, v8
	s_add_u32 s25, s48, 0x14e00000
	v_add_u32_e32 v0, s9, v0
	v_bitop3_b32 v4, v2, v15, 2 bitop3:0x36
	v_lshl_add_u32 v8, v12, 12, v8
	v_and_b32_e32 v9, 1, v13
	s_addc_u32 s26, s49, 0
	v_xor_b32_e32 v3, v2, v15
	v_lshl_add_u32 v5, v4, 4, v0
	v_bitop3_b32 v4, v2, v15, 4 bitop3:0x36
	v_bitop3_b32 v2, v2, v15, 6 bitop3:0x36
	v_lshl_or_b32 v8, v9, 6, v8
	v_and_b32_e32 v159, 63, v10
	v_lshlrev_b32_e32 v16, 3, v15
	s_add_u32 s27, s48, 0xae00000
	v_lshlrev_b32_e32 v1, 10, v15
	v_lshl_add_u32 v15, v2, 4, v0
	v_and_b32_e32 v2, 7, v10
	v_bfe_u32 v10, v10, 3, 3
	v_mov_b32_e32 v140, v236
	v_mbcnt_lo_u32_b32 v8, -1, 0
	s_waitcnt vmcnt(6)
	s_addc_u32 s28, s49, 0
	s_lshl_b32 s8, s8, 21
	v_lshl_add_u32 v3, v3, 4, v0
	v_lshl_add_u32 v7, v4, 4, v0
	v_lshlrev_b32_e32 v0, 3, v2
	v_lshl_add_u32 v17, v10, 7, s9
	v_lshlrev_b32_e32 v18, 4, v2
	v_lshlrev_b32_e32 v2, 15, v10
	v_or_b32_e32 v4, 8, v10
	v_or_b32_e32 v6, 16, v10
	v_or_b32_e32 v10, 24, v10
	v_mbcnt_hi_u32_b32 v8, -1, v8
	v_lshl_add_u32 v20, v4, 7, s9
	v_xor_b32_e32 v21, 16, v18
	v_lshlrev_b32_e32 v4, 15, v4
	v_lshl_add_u32 v22, v6, 7, s9
	v_xor_b32_e32 v23, 32, v18
	v_lshlrev_b32_e32 v6, 15, v6
	v_lshl_add_u32 v24, v10, 7, s9
	v_xor_b32_e32 v25, 48, v18
	v_lshlrev_b32_e32 v10, 15, v10
	s_or_b32 s9, s8, 0x100000
	s_add_i32 s30, 0, 0x10000
	s_add_i32 s31, 0, 0x14000
	v_and_or_b32 v8, v8, 64, v157
	s_ashr_i32 s29, s3, 31
	v_mov_b32_e32 v139, v137
	v_mov_b32_e32 v141, v137
	v_mov_b32_e32 v163, v240
	v_lshlrev_b32_e32 v165, 2, v8
	s_mov_b32 s34, 0x800000
	v_lshlrev_b32_e32 v136, 1, v0
	v_add_u32_e32 v167, v3, v1
	v_add_u32_e32 v169, v5, v1
	v_add_u32_e32 v171, v7, v1
	v_add_u32_e32 v173, v15, v1
	s_lshl_b32 s54, s8, 1
	v_add_u32_e32 v184, v17, v18
	v_lshlrev_b32_e32 v142, 1, v2
	v_add_u32_e32 v185, v20, v21
	v_lshlrev_b32_e32 v144, 1, v4
	v_add_u32_e32 v186, v22, v23
	v_lshlrev_b32_e32 v146, 1, v6
	v_add_u32_e32 v187, v24, v25
	v_lshlrev_b32_e32 v148, 1, v10
	s_lshl_b32 s56, s9, 1
	s_lshl_b32 s35, s11, 1
	v_lshlrev_b32_e32 v150, 1, v16
	v_mov_b64_e32 v[152:153], 0xa00
	v_mov_b64_e32 v[154:155], 0x9ff
	v_add_u32_e32 v188, s30, v161
	v_add_u32_e32 v189, 0x11000, v161
	v_mov_b32_e32 v156, 0x358637bd
	s_mov_b32 s38, 0
	s_barrier
	s_branch .LBB0_960

; #define PG8_STAGE(bufoff, gbase, voff) do { _Pragma("unroll") for (int _i = 0; _i < 2; ++_i) \
;         __builtin_amdgcn_global_load_lds((const unsigned*)((const char*)(gbase) + (voff)[_i]), (LAS unsigned*)(lds + (bufoff) + ldsw + _i * 8192), 16, 0, 0); } while (0)
; #define PG8_LDA(dst, b, h) do { _Pragma("unroll") for (int m = 0; m < 4; ++m) _Pragma("unroll") for (int k = 0; k < 2; ++k) dst[m][k] = *(const LAS bf16x8*)(lds + PG8_SA(b, h) + aoff + m * 2048 + k * 1024); } while (0)
; #define PG8_LDB(dst, b, h) do { _Pragma("unroll") for (int n = 0; n < 2; ++n) _Pragma("unroll") for (int k = 0; k < 2; ++k) dst[n][k] = *(const LAS bf16x8*)(lds + PG8_SB(b, h) + boff + n * 2048 + k * 1024); } while (0)
; #define PG8_MMA(ai, bj, At, Bt) do { __builtin_amdgcn_s_setprio(1); _Pragma("unroll") for (int m = 0; m < 4; ++m) _Pragma("unroll") for (int n = 0; n < 2; ++n) _Pragma("unroll") for (int k = 0; k < 2; ++k) \
;         acc[ai][bj][m][n] = __builtin_amdgcn_mfma_f32_16x16x32_bf16(Bt[n][k], At[m][k], acc[ai][bj][m][n], 0, 0, 0); __builtin_amdgcn_s_setprio(0); } while (0)
; #define PG8_WAIT_V(n) asm volatile("s_waitcnt vmcnt(" #n ")" ::: "memory")
; #define PG8_WAIT_L(n) asm volatile("s_waitcnt lgkmcnt(" #n ")" ::: "memory")
; #define PG8_BAR __builtin_amdgcn_s_barrier()
; #define PG8_SCHED __builtin_amdgcn_sched_barrier(0)
; template <class Epi, class Sched>
; __device__ __forceinline__ void gemm_phase(LAS unsigned char* lds, const int K, const int lda, const int ldb, const Sched& S, const Epi& E) {
;     ...
;             PG8_LDB(B0, 0, 0); PG8_LDB(B1, 0, 1); PG8_SCHED; PG8_LDA(At, 0, 0); PG8_STAGE(PG8_SA(1, 1), a1 + hA, voffA);
;             PG8_WAIT_V(8); PG8_WAIT_L(0); PG8_BAR; PG8_MMA(0, 0, At, B0); PG8_MMA(0, 1, At, B1); PG8_BAR; PG8_SCHED;
;     ...
;         for (int a = 0; a < 2; ++a)
; #pragma unroll
;             for (int b = 0; b < 2; ++b)
; #pragma unroll
;                 for (int m = 0; m < 4; ++m)
; #pragma unroll
;                     for (int n = 0; n < 2; ++n) acc[a][b][m][n] = (f32x4){0.f, 0.f, 0.f, 0.f};
;         cur = nxt; cA = nA; cB = nB; ++ui;
.LBB0_962:
	v_xor_b32_e32 v145, 64, v163
	v_xor_b32_e32 v147, 64, v188
	v_xor_b32_e32 v149, 64, v189
	v_xor_b32_e32 v151, 64, v161
	s_ashr_i32 s61, s60, 31
	s_lshl_b64 s[62:63], s[60:61], 20
	s_add_u32 s62, s42, s62
	s_addc_u32 s63, s43, s63
	s_and_b64 s[64:65], s[8:9], exec
	s_cselect_b32 s11, s63, s69
	s_cselect_b32 s18, s62, s68
	s_ashr_i32 s59, s58, 31
	s_lshl_b64 s[64:65], s[58:59], 20
	s_add_u32 s64, s12, s64
	s_addc_u32 s65, s13, s65
	s_and_b64 s[70:71], s[8:9], exec
	s_cselect_b32 s39, s65, s67
	s_cselect_b32 s41, s64, s66
	s_add_u32 s55, s66, 0x100
	s_addc_u32 s57, s67, 0
	s_add_u32 s66, s68, 0x80080
	v_mov_b32_e32 v0, 0
	s_addc_u32 s67, s69, 0
	s_mov_b32 s59, -2
	v_mov_b32_e32 v1, v0
	v_mov_b32_e32 v2, v0
	v_mov_b32_e32 v3, v0
	v_mov_b32_e32 v4, v0
	v_mov_b32_e32 v5, v0
	v_mov_b32_e32 v6, v0
	v_mov_b32_e32 v7, v0
	v_mov_b32_e32 v16, v0
	v_mov_b32_e32 v17, v0
	v_mov_b32_e32 v18, v0
	v_mov_b32_e32 v19, v0
	v_mov_b32_e32 v20, v0
	v_mov_b32_e32 v21, v0
	v_mov_b32_e32 v22, v0
	v_mov_b32_e32 v23, v0
	v_mov_b32_e32 v32, v0
	v_mov_b32_e32 v33, v0
	v_mov_b32_e32 v34, v0
	v_mov_b32_e32 v35, v0
	v_mov_b32_e32 v36, v0
	v_mov_b32_e32 v37, v0
	v_mov_b32_e32 v38, v0
	v_mov_b32_e32 v39, v0
	v_mov_b32_e32 v48, v0
	v_mov_b32_e32 v49, v0
	v_mov_b32_e32 v50, v0
	v_mov_b32_e32 v51, v0
	v_mov_b32_e32 v52, v0
	v_mov_b32_e32 v53, v0
	v_mov_b32_e32 v54, v0
	v_mov_b32_e32 v55, v0
	v_mov_b32_e32 v8, v0
	v_mov_b32_e32 v9, v0
	v_mov_b32_e32 v10, v0
	v_mov_b32_e32 v11, v0
	v_mov_b32_e32 v12, v0
	v_mov_b32_e32 v13, v0
	v_mov_b32_e32 v14, v0
	v_mov_b32_e32 v15, v0
	v_mov_b32_e32 v24, v0
	v_mov_b32_e32 v25, v0
	v_mov_b32_e32 v26, v0
	v_mov_b32_e32 v27, v0
	v_mov_b32_e32 v28, v0
	v_mov_b32_e32 v29, v0
	v_mov_b32_e32 v30, v0
	v_mov_b32_e32 v31, v0
	v_mov_b32_e32 v40, v0
	v_mov_b32_e32 v41, v0
	v_mov_b32_e32 v42, v0
	v_mov_b32_e32 v43, v0
	v_mov_b32_e32 v44, v0
	v_mov_b32_e32 v45, v0
	v_mov_b32_e32 v46, v0
	v_mov_b32_e32 v47, v0
	v_mov_b32_e32 v56, v0
	v_mov_b32_e32 v57, v0
	v_mov_b32_e32 v58, v0
	v_mov_b32_e32 v59, v0
	v_mov_b32_e32 v60, v0
	v_mov_b32_e32 v61, v0
	v_mov_b32_e32 v62, v0
	v_mov_b32_e32 v63, v0
	v_mov_b32_e32 v64, v0
	v_mov_b32_e32 v65, v0
	v_mov_b32_e32 v66, v0
	v_mov_b32_e32 v67, v0
	v_mov_b32_e32 v68, v0
	v_mov_b32_e32 v69, v0
	v_mov_b32_e32 v70, v0
	v_mov_b32_e32 v71, v0
	v_mov_b32_e32 v80, v0
	v_mov_b32_e32 v81, v0
	v_mov_b32_e32 v82, v0
	v_mov_b32_e32 v83, v0
	v_mov_b32_e32 v84, v0
	v_mov_b32_e32 v85, v0
	v_mov_b32_e32 v86, v0
	v_mov_b32_e32 v87, v0
	v_mov_b32_e32 v96, v0
	v_mov_b32_e32 v97, v0
	v_mov_b32_e32 v98, v0
	v_mov_b32_e32 v99, v0
	v_mov_b32_e32 v100, v0
	v_mov_b32_e32 v101, v0
	v_mov_b32_e32 v102, v0
	v_mov_b32_e32 v103, v0
	v_mov_b32_e32 v112, v0
	v_mov_b32_e32 v113, v0
	v_mov_b32_e32 v114, v0
	v_mov_b32_e32 v115, v0
	v_mov_b32_e32 v116, v0
	v_mov_b32_e32 v117, v0
	v_mov_b32_e32 v118, v0
	v_mov_b32_e32 v119, v0
	v_mov_b32_e32 v72, v0
	v_mov_b32_e32 v73, v0
	v_mov_b32_e32 v74, v0
	v_mov_b32_e32 v75, v0
	v_mov_b32_e32 v76, v0
	v_mov_b32_e32 v77, v0
	v_mov_b32_e32 v78, v0
	v_mov_b32_e32 v79, v0
	v_mov_b32_e32 v88, v0
	v_mov_b32_e32 v89, v0
	v_mov_b32_e32 v90, v0
	v_mov_b32_e32 v91, v0
	v_mov_b32_e32 v92, v0
	v_mov_b32_e32 v93, v0
	v_mov_b32_e32 v94, v0
	v_mov_b32_e32 v95, v0
	v_mov_b32_e32 v104, v0
	v_mov_b32_e32 v105, v0
	v_mov_b32_e32 v106, v0
	v_mov_b32_e32 v107, v0
	v_mov_b32_e32 v108, v0
	v_mov_b32_e32 v109, v0
	v_mov_b32_e32 v110, v0
	v_mov_b32_e32 v111, v0
	v_mov_b32_e32 v120, v0
	v_mov_b32_e32 v121, v0
	v_mov_b32_e32 v122, v0
	v_mov_b32_e32 v123, v0
	v_mov_b32_e32 v124, v0
	v_mov_b32_e32 v125, v0
	v_mov_b32_e32 v126, v0
	v_mov_b32_e32 v127, v0
.LBB0_963:
	ds_read_b128 v[174:177], v188
	ds_read_b128 v[178:181], v147
	ds_read_b128 v[190:193], v188 offset:2048
	ds_read_b128 v[194:197], v147 offset:2048
	ds_read_b128 v[198:201], v189
	ds_read_b128 v[202:205], v149
	ds_read_b128 v[206:209], v189 offset:2048
	ds_read_b128 v[210:213], v149 offset:2048
	s_add_u32 s61, s66, 0xfff80080
	s_addc_u32 s68, s67, -1
	s_cmp_eq_u32 s59, 28
	s_cselect_b32 s71, s11, s68
	s_cselect_b32 s70, s18, s61
	s_cselect_b32 s69, s39, s57
	s_cselect_b32 s68, s41, s55
	v_lshl_add_u64 v[182:183], s[66:67], 0, v[140:141]
	s_add_i32 m0, s1, 0xc000
	ds_read_b128 v[214:217], v163
	ds_read_b128 v[218:221], v145
	ds_read_b128 v[222:225], v163 offset:2048
	ds_read_b128 v[226:229], v145 offset:2048
	ds_read_b128 v[230:233], v163 offset:4096
	ds_read_b128 v[236:239], v145 offset:4096
	ds_read_b128 v[240:243], v163 offset:6144
	ds_read_b128 v[244:247], v145 offset:6144
	global_load_lds_dwordx4 v[182:183], off
	v_lshl_add_u64 v[182:183], s[66:67], 0, v[138:139]
	s_add_i32 m0, s1, 0xe000
	s_nop 0
	global_load_lds_dwordx4 v[182:183], off
	s_waitcnt vmcnt(8)
	s_waitcnt lgkmcnt(0)
	s_barrier
; #define PG8_STAGE(bufoff, gbase, voff) do { _Pragma("unroll") for (int _i = 0; _i < 2; ++_i) \
;         __builtin_amdgcn_global_load_lds((const unsigned*)((const char*)(gbase) + (voff)[_i]), (LAS unsigned*)(lds + (bufoff) + ldsw + _i * 8192), 16, 0, 0); } while (0)
; #define PG8_LDA(dst, b, h) do { _Pragma("unroll") for (int m = 0; m < 4; ++m) _Pragma("unroll") for (int k = 0; k < 2; ++k) dst[m][k] = *(const LAS bf16x8*)(lds + PG8_SA(b, h) + aoff + m * 2048 + k * 1024); } while (0)
; #define PG8_MMA(ai, bj, At, Bt) do { __builtin_amdgcn_s_setprio(1); _Pragma("unroll") for (int m = 0; m < 4; ++m) _Pragma("unroll") for (int n = 0; n < 2; ++n) _Pragma("unroll") for (int k = 0; k < 2; ++k) \
;         acc[ai][bj][m][n] = __builtin_amdgcn_mfma_f32_16x16x32_bf16(Bt[n][k], At[m][k], acc[ai][bj][m][n], 0, 0, 0); __builtin_amdgcn_s_setprio(0); } while (0)
; #define PG8_WAIT_V(n) asm volatile("s_waitcnt vmcnt(" #n ")" ::: "memory")
; #define PG8_WAIT_L(n) asm volatile("s_waitcnt lgkmcnt(" #n ")" ::: "memory")
; #define PG8_BAR __builtin_amdgcn_s_barrier()
; #define PG8_SCHED __builtin_amdgcn_sched_barrier(0)
; template <class Epi, class Sched>
; __device__ __forceinline__ void gemm_phase(LAS unsigned char* lds, const int K, const int lda, const int ldb, const Sched& S, const Epi& E) {
;     ...
;             PG8_WAIT_V(8); PG8_WAIT_L(0); PG8_BAR; PG8_MMA(0, 0, At, B0); PG8_MMA(0, 1, At, B1); PG8_BAR; PG8_SCHED;
;             PG8_LDA(At, 0, 1); PG8_STAGE(PG8_SB(0, 0), b2, voffB); PG8_STAGE(PG8_SB(0, 1), b2 + hB, voffB); PG8_STAGE(PG8_SA(0, 0), a2, voffA);
;             PG8_WAIT_V(8); PG8_WAIT_L(0); PG8_BAR; PG8_MMA(1, 0, At, B0); PG8_MMA(1, 1, At, B1); PG8_BAR; PG8_SCHED;
	s_setprio 1
	s_waitcnt lgkmcnt(0)
	v_mfma_f32_16x16x32_bf16 v[124:127], v[174:177], v[214:217], v[124:127]
	v_mfma_f32_16x16x32_bf16 v[120:123], v[190:193], v[214:217], v[120:123]
	v_mfma_f32_16x16x32_bf16 v[108:111], v[174:177], v[222:225], v[108:111]
	v_mfma_f32_16x16x32_bf16 v[104:107], v[190:193], v[222:225], v[104:107]
	v_mfma_f32_16x16x32_bf16 v[92:95], v[174:177], v[230:233], v[92:95]
	v_mfma_f32_16x16x32_bf16 v[88:91], v[190:193], v[230:233], v[88:91]
	v_mfma_f32_16x16x32_bf16 v[76:79], v[174:177], v[240:243], v[76:79]
	v_mfma_f32_16x16x32_bf16 v[72:75], v[190:193], v[240:243], v[72:75]
	v_mfma_f32_16x16x32_bf16 v[124:127], v[178:181], v[218:221], v[124:127]
	v_mfma_f32_16x16x32_bf16 v[120:123], v[194:197], v[218:221], v[120:123]
	v_mfma_f32_16x16x32_bf16 v[108:111], v[178:181], v[226:229], v[108:111]
	v_mfma_f32_16x16x32_bf16 v[104:107], v[194:197], v[226:229], v[104:107]
	v_mfma_f32_16x16x32_bf16 v[92:95], v[178:181], v[236:239], v[92:95]
	v_mfma_f32_16x16x32_bf16 v[88:91], v[194:197], v[236:239], v[88:91]
	v_mfma_f32_16x16x32_bf16 v[76:79], v[178:181], v[244:247], v[76:79]
	v_mfma_f32_16x16x32_bf16 v[72:75], v[194:197], v[244:247], v[72:75]
	s_setprio 0
	s_setprio 1
	v_mfma_f32_16x16x32_bf16 v[116:119], v[198:201], v[214:217], v[116:119]
	v_mfma_f32_16x16x32_bf16 v[112:115], v[206:209], v[214:217], v[112:115]
	v_mfma_f32_16x16x32_bf16 v[100:103], v[198:201], v[222:225], v[100:103]
	v_mfma_f32_16x16x32_bf16 v[96:99], v[206:209], v[222:225], v[96:99]
	v_mfma_f32_16x16x32_bf16 v[84:87], v[198:201], v[230:233], v[84:87]
	v_mfma_f32_16x16x32_bf16 v[80:83], v[206:209], v[230:233], v[80:83]
	v_mfma_f32_16x16x32_bf16 v[68:71], v[198:201], v[240:243], v[68:71]
	v_mfma_f32_16x16x32_bf16 v[64:67], v[206:209], v[240:243], v[64:67]
	v_mfma_f32_16x16x32_bf16 v[116:119], v[202:205], v[218:221], v[116:119]
	v_mfma_f32_16x16x32_bf16 v[112:115], v[210:213], v[218:221], v[112:115]
	v_mfma_f32_16x16x32_bf16 v[100:103], v[202:205], v[226:229], v[100:103]
	v_mfma_f32_16x16x32_bf16 v[96:99], v[210:213], v[226:229], v[96:99]
	v_mfma_f32_16x16x32_bf16 v[84:87], v[202:205], v[236:239], v[84:87]
	v_mfma_f32_16x16x32_bf16 v[80:83], v[210:213], v[236:239], v[80:83]
	v_mfma_f32_16x16x32_bf16 v[68:71], v[202:205], v[244:247], v[68:71]
	v_mfma_f32_16x16x32_bf16 v[64:67], v[210:213], v[244:247], v[64:67]
	s_setprio 0
	s_barrier
	s_add_i32 s61, s30, s2
	v_lshl_add_u64 v[182:183], s[68:69], 0, v[132:133]
	s_mov_b32 m0, s61
	ds_read_b128 v[214:217], v163 offset:16384
	ds_read_b128 v[218:221], v145 offset:16384
	ds_read_b128 v[222:225], v163 offset:18432
	ds_read_b128 v[226:229], v145 offset:18432
	ds_read_b128 v[230:233], v163 offset:20480
	ds_read_b128 v[236:239], v145 offset:20480
	ds_read_b128 v[240:243], v163 offset:22528
	ds_read_b128 v[244:247], v145 offset:22528
	global_load_lds_dwordx4 v[182:183], off
	s_add_i32 m0, s61, 0x2000
	s_add_u32 s72, s68, 0x80000
	v_lshl_add_u64 v[234:235], s[68:69], 0, v[128:129]
	s_addc_u32 s73, s69, 0
	s_add_i32 s61, s31, s2
	global_load_lds_dwordx4 v[234:235], off
	v_lshl_add_u64 v[248:249], s[72:73], 0, v[132:133]
	s_mov_b32 m0, s61
	v_lshl_add_u64 v[250:251], s[70:71], 0, v[130:131]
	global_load_lds_dwordx4 v[248:249], off
	v_lshl_add_u64 v[248:249], s[72:73], 0, v[128:129]
	s_add_i32 m0, s61, 0x2000
	s_nop 0
	global_load_lds_dwordx4 v[248:249], off
	v_lshl_add_u64 v[248:249], s[70:71], 0, v[134:135]
	s_mov_b32 m0, s1
	s_nop 0
	global_load_lds_dwordx4 v[248:249], off
	s_mov_b32 m0, s6
	s_nop 0
	global_load_lds_dwordx4 v[250:251], off
	s_waitcnt vmcnt(8)
	s_waitcnt lgkmcnt(0)
	s_barrier
	s_setprio 1
	s_waitcnt lgkmcnt(0)
	v_mfma_f32_16x16x32_bf16 v[60:63], v[174:177], v[214:217], v[60:63]
	v_mfma_f32_16x16x32_bf16 v[56:59], v[190:193], v[214:217], v[56:59]
	v_mfma_f32_16x16x32_bf16 v[44:47], v[174:177], v[222:225], v[44:47]
	v_mfma_f32_16x16x32_bf16 v[40:43], v[190:193], v[222:225], v[40:43]
	v_mfma_f32_16x16x32_bf16 v[28:31], v[174:177], v[230:233], v[28:31]
	v_mfma_f32_16x16x32_bf16 v[24:27], v[190:193], v[230:233], v[24:27]
	v_mfma_f32_16x16x32_bf16 v[12:15], v[174:177], v[240:243], v[12:15]
	v_mfma_f32_16x16x32_bf16 v[8:11], v[190:193], v[240:243], v[8:11]
	v_mfma_f32_16x16x32_bf16 v[60:63], v[178:181], v[218:221], v[60:63]
	v_mfma_f32_16x16x32_bf16 v[56:59], v[194:197], v[218:221], v[56:59]
	v_mfma_f32_16x16x32_bf16 v[44:47], v[178:181], v[226:229], v[44:47]
	v_mfma_f32_16x16x32_bf16 v[40:43], v[194:197], v[226:229], v[40:43]
	v_mfma_f32_16x16x32_bf16 v[28:31], v[178:181], v[236:239], v[28:31]
	v_mfma_f32_16x16x32_bf16 v[24:27], v[194:197], v[236:239], v[24:27]
	v_mfma_f32_16x16x32_bf16 v[12:15], v[178:181], v[244:247], v[12:15]
	v_mfma_f32_16x16x32_bf16 v[8:11], v[194:197], v[244:247], v[8:11]
	s_setprio 0
	s_setprio 1
	v_mfma_f32_16x16x32_bf16 v[52:55], v[198:201], v[214:217], v[52:55]
	v_mfma_f32_16x16x32_bf16 v[48:51], v[206:209], v[214:217], v[48:51]
	v_mfma_f32_16x16x32_bf16 v[36:39], v[198:201], v[222:225], v[36:39]
	v_mfma_f32_16x16x32_bf16 v[32:35], v[206:209], v[222:225], v[32:35]
	v_mfma_f32_16x16x32_bf16 v[20:23], v[198:201], v[230:233], v[20:23]
	v_mfma_f32_16x16x32_bf16 v[16:19], v[206:209], v[230:233], v[16:19]
	v_mfma_f32_16x16x32_bf16 v[4:7], v[198:201], v[240:243], v[4:7]
	v_mfma_f32_16x16x32_bf16 v[0:3], v[206:209], v[240:243], v[0:3]
	v_mfma_f32_16x16x32_bf16 v[52:55], v[202:205], v[218:221], v[52:55]
	v_mfma_f32_16x16x32_bf16 v[48:51], v[210:213], v[218:221], v[48:51]
	v_mfma_f32_16x16x32_bf16 v[36:39], v[202:205], v[226:229], v[36:39]
	v_mfma_f32_16x16x32_bf16 v[32:35], v[210:213], v[226:229], v[32:35]
	v_mfma_f32_16x16x32_bf16 v[20:23], v[202:205], v[236:239], v[20:23]
	v_mfma_f32_16x16x32_bf16 v[16:19], v[210:213], v[236:239], v[16:19]
	v_mfma_f32_16x16x32_bf16 v[4:7], v[202:205], v[244:247], v[4:7]
	v_mfma_f32_16x16x32_bf16 v[0:3], v[210:213], v[244:247], v[0:3]
	s_setprio 0
	s_barrier
; #define PG8_STAGE(bufoff, gbase, voff) do { _Pragma("unroll") for (int _i = 0; _i < 2; ++_i) \
;         __builtin_amdgcn_global_load_lds((const unsigned*)((const char*)(gbase) + (voff)[_i]), (LAS unsigned*)(lds + (bufoff) + ldsw + _i * 8192), 16, 0, 0); } while (0)
; #define PG8_LDA(dst, b, h) do { _Pragma("unroll") for (int m = 0; m < 4; ++m) _Pragma("unroll") for (int k = 0; k < 2; ++k) dst[m][k] = *(const LAS bf16x8*)(lds + PG8_SA(b, h) + aoff + m * 2048 + k * 1024); } while (0)
; #define PG8_LDB(dst, b, h) do { _Pragma("unroll") for (int n = 0; n < 2; ++n) _Pragma("unroll") for (int k = 0; k < 2; ++k) dst[n][k] = *(const LAS bf16x8*)(lds + PG8_SB(b, h) + boff + n * 2048 + k * 1024); } while (0)
; #define PG8_MMA(ai, bj, At, Bt) do { __builtin_amdgcn_s_setprio(1); _Pragma("unroll") for (int m = 0; m < 4; ++m) _Pragma("unroll") for (int n = 0; n < 2; ++n) _Pragma("unroll") for (int k = 0; k < 2; ++k) \
;         acc[ai][bj][m][n] = __builtin_amdgcn_mfma_f32_16x16x32_bf16(Bt[n][k], At[m][k], acc[ai][bj][m][n], 0, 0, 0); __builtin_amdgcn_s_setprio(0); } while (0)
; #define PG8_WAIT_V(n) asm volatile("s_waitcnt vmcnt(" #n ")" ::: "memory")
; #define PG8_WAIT_L(n) asm volatile("s_waitcnt lgkmcnt(" #n ")" ::: "memory")
; #define PG8_BAR __builtin_amdgcn_s_barrier()
; #define PG8_SCHED __builtin_amdgcn_sched_barrier(0)
; template <class Epi, class Sched>
; __device__ __forceinline__ void gemm_phase(LAS unsigned char* lds, const int K, const int lda, const int ldb, const Sched& S, const Epi& E) {
;     ...
;             PG8_LDB(B0, 1, 0); PG8_LDB(B1, 1, 1); PG8_SCHED; PG8_LDA(At, 1, 0); PG8_STAGE(PG8_SA(0, 1), a2 + hA, voffA);
;             PG8_WAIT_V(8); PG8_WAIT_L(0); PG8_BAR; PG8_MMA(0, 0, At, B0); PG8_MMA(0, 1, At, B1); PG8_BAR; PG8_SCHED;
	s_add_i32 s61, 0, 0x18000
	v_add_u32_e32 v143, s61, v161
	v_add_u32_e32 v158, s61, v151
	s_add_i32 s72, 0, 0x1c000
	ds_read_b128 v[174:177], v143
	ds_read_b128 v[178:181], v158
	ds_read_b128 v[190:193], v143 offset:2048
	ds_read_b128 v[194:197], v158 offset:2048
	v_add_u32_e32 v143, 0x19000, v161
	v_add_u32_e32 v158, 0x19000, v151
	ds_read_b128 v[198:201], v143
	ds_read_b128 v[202:205], v158
	ds_read_b128 v[206:209], v143 offset:2048
	ds_read_b128 v[210:213], v158 offset:2048
	s_add_u32 s70, s70, 0x80000
	s_addc_u32 s71, s71, 0
	s_mov_b32 m0, s7
	v_lshl_add_u64 v[252:253], s[70:71], 0, v[134:135]
	ds_read_b128 v[214:217], v163 offset:32768
	ds_read_b128 v[218:221], v145 offset:32768
	ds_read_b128 v[222:225], v163 offset:34816
	ds_read_b128 v[226:229], v145 offset:34816
	ds_read_b128 v[230:233], v163 offset:36864
	ds_read_b128 v[236:239], v145 offset:36864
	ds_read_b128 v[240:243], v163 offset:38912
	ds_read_b128 v[244:247], v145 offset:38912
	global_load_lds_dwordx4 v[252:253], off
	v_lshl_add_u64 v[252:253], s[70:71], 0, v[130:131]
	s_mov_b32 m0, s14
	s_nop 0
	global_load_lds_dwordx4 v[252:253], off
	s_waitcnt vmcnt(8)
	s_waitcnt lgkmcnt(0)
	s_barrier
	s_setprio 1
	s_waitcnt lgkmcnt(0)
	v_mfma_f32_16x16x32_bf16 v[124:127], v[174:177], v[214:217], v[124:127]
	v_mfma_f32_16x16x32_bf16 v[120:123], v[190:193], v[214:217], v[120:123]
	v_mfma_f32_16x16x32_bf16 v[108:111], v[174:177], v[222:225], v[108:111]
	v_mfma_f32_16x16x32_bf16 v[104:107], v[190:193], v[222:225], v[104:107]
	v_mfma_f32_16x16x32_bf16 v[92:95], v[174:177], v[230:233], v[92:95]
	v_mfma_f32_16x16x32_bf16 v[88:91], v[190:193], v[230:233], v[88:91]
	v_mfma_f32_16x16x32_bf16 v[76:79], v[174:177], v[240:243], v[76:79]
	v_mfma_f32_16x16x32_bf16 v[72:75], v[190:193], v[240:243], v[72:75]
	v_mfma_f32_16x16x32_bf16 v[124:127], v[178:181], v[218:221], v[124:127]
	v_mfma_f32_16x16x32_bf16 v[120:123], v[194:197], v[218:221], v[120:123]
	v_mfma_f32_16x16x32_bf16 v[108:111], v[178:181], v[226:229], v[108:111]
	v_mfma_f32_16x16x32_bf16 v[104:107], v[194:197], v[226:229], v[104:107]
	v_mfma_f32_16x16x32_bf16 v[92:95], v[178:181], v[236:239], v[92:95]
	v_mfma_f32_16x16x32_bf16 v[88:91], v[194:197], v[236:239], v[88:91]
	v_mfma_f32_16x16x32_bf16 v[76:79], v[178:181], v[244:247], v[76:79]
	v_mfma_f32_16x16x32_bf16 v[72:75], v[194:197], v[244:247], v[72:75]
	s_setprio 0
	s_setprio 1
	v_mfma_f32_16x16x32_bf16 v[116:119], v[198:201], v[214:217], v[116:119]
	v_mfma_f32_16x16x32_bf16 v[112:115], v[206:209], v[214:217], v[112:115]
	v_mfma_f32_16x16x32_bf16 v[100:103], v[198:201], v[222:225], v[100:103]
	v_mfma_f32_16x16x32_bf16 v[96:99], v[206:209], v[222:225], v[96:99]
	v_mfma_f32_16x16x32_bf16 v[84:87], v[198:201], v[230:233], v[84:87]
	v_mfma_f32_16x16x32_bf16 v[80:83], v[206:209], v[230:233], v[80:83]
	v_mfma_f32_16x16x32_bf16 v[68:71], v[198:201], v[240:243], v[68:71]
	v_mfma_f32_16x16x32_bf16 v[64:67], v[206:209], v[240:243], v[64:67]
	v_mfma_f32_16x16x32_bf16 v[116:119], v[202:205], v[218:221], v[116:119]
	v_mfma_f32_16x16x32_bf16 v[112:115], v[210:213], v[218:221], v[112:115]
	v_mfma_f32_16x16x32_bf16 v[100:103], v[202:205], v[226:229], v[100:103]
	v_mfma_f32_16x16x32_bf16 v[96:99], v[210:213], v[226:229], v[96:99]
	v_mfma_f32_16x16x32_bf16 v[84:87], v[202:205], v[236:239], v[84:87]
	v_mfma_f32_16x16x32_bf16 v[80:83], v[210:213], v[236:239], v[80:83]
	v_mfma_f32_16x16x32_bf16 v[68:71], v[202:205], v[244:247], v[68:71]
	v_mfma_f32_16x16x32_bf16 v[64:67], v[210:213], v[244:247], v[64:67]
	s_setprio 0
	s_barrier
; #define PG8_STAGE(bufoff, gbase, voff) do { _Pragma("unroll") for (int _i = 0; _i < 2; ++_i) \
;         __builtin_amdgcn_global_load_lds((const unsigned*)((const char*)(gbase) + (voff)[_i]), (LAS unsigned*)(lds + (bufoff) + ldsw + _i * 8192), 16, 0, 0); } while (0)
; #define PG8_LDA(dst, b, h) do { _Pragma("unroll") for (int m = 0; m < 4; ++m) _Pragma("unroll") for (int k = 0; k < 2; ++k) dst[m][k] = *(const LAS bf16x8*)(lds + PG8_SA(b, h) + aoff + m * 2048 + k * 1024); } while (0)
; #define PG8_MMA(ai, bj, At, Bt) do { __builtin_amdgcn_s_setprio(1); _Pragma("unroll") for (int m = 0; m < 4; ++m) _Pragma("unroll") for (int n = 0; n < 2; ++n) _Pragma("unroll") for (int k = 0; k < 2; ++k) \
;         acc[ai][bj][m][n] = __builtin_amdgcn_mfma_f32_16x16x32_bf16(Bt[n][k], At[m][k], acc[ai][bj][m][n], 0, 0, 0); __builtin_amdgcn_s_setprio(0); } while (0)
; #define PG8_WAIT_V(n) asm volatile("s_waitcnt vmcnt(" #n ")" ::: "memory")
; #define PG8_WAIT_L(n) asm volatile("s_waitcnt lgkmcnt(" #n ")" ::: "memory")
; #define PG8_BAR __builtin_amdgcn_s_barrier()
; #define PG8_SCHED __builtin_amdgcn_sched_barrier(0)
; template <class Epi, class Sched>
; __device__ __forceinline__ void gemm_phase(LAS unsigned char* lds, const int K, const int lda, const int ldb, const Sched& S, const Epi& E) {
;     ...
;             PG8_LDA(At, 1, 1); PG8_STAGE(PG8_SB(1, 0), b3, voffB); PG8_STAGE(PG8_SB(1, 1), b3 + hB, voffB); PG8_STAGE(PG8_SA(1, 0), a3, voffA);
;             PG8_WAIT_V(8); PG8_WAIT_L(0); PG8_BAR; PG8_MMA(1, 0, At, B0); PG8_MMA(1, 1, At, B1); PG8_BAR; PG8_SCHED;
;         }
	s_add_i32 s61, s61, s2
	v_lshl_add_u64 v[182:183], v[182:183], 0, s[50:51]
	s_mov_b32 m0, s61
	ds_read_b128 v[214:217], v163 offset:49152
	ds_read_b128 v[218:221], v145 offset:49152
	ds_read_b128 v[222:225], v163 offset:51200
	ds_read_b128 v[226:229], v145 offset:51200
	ds_read_b128 v[230:233], v163 offset:53248
	ds_read_b128 v[236:239], v145 offset:53248
	ds_read_b128 v[240:243], v163 offset:55296
	ds_read_b128 v[244:247], v145 offset:55296
	global_load_lds_dwordx4 v[182:183], off
	s_add_i32 m0, s61, 0x2000
	s_add_u32 s68, s68, 0x80080
	v_lshl_add_u64 v[182:183], v[234:235], 0, s[50:51]
	s_addc_u32 s69, s69, 0
	s_add_i32 s61, s72, s2
	global_load_lds_dwordx4 v[182:183], off
	v_lshl_add_u64 v[182:183], s[68:69], 0, v[132:133]
	s_mov_b32 m0, s61
	s_nop 0
	global_load_lds_dwordx4 v[182:183], off
	v_lshl_add_u64 v[182:183], s[68:69], 0, v[128:129]
	s_add_i32 m0, s61, 0x2000
	s_nop 0
	global_load_lds_dwordx4 v[182:183], off
	v_lshl_add_u64 v[182:183], v[248:249], 0, s[50:51]
	s_mov_b32 m0, s17
	s_nop 0
	global_load_lds_dwordx4 v[182:183], off
	v_lshl_add_u64 v[182:183], v[250:251], 0, s[50:51]
	s_mov_b32 m0, s21
	s_nop 0
	global_load_lds_dwordx4 v[182:183], off
	s_waitcnt vmcnt(8)
	s_waitcnt lgkmcnt(0)
	s_barrier
	s_setprio 1
	s_waitcnt lgkmcnt(0)
	v_mfma_f32_16x16x32_bf16 v[60:63], v[174:177], v[214:217], v[60:63]
	v_mfma_f32_16x16x32_bf16 v[56:59], v[190:193], v[214:217], v[56:59]
	v_mfma_f32_16x16x32_bf16 v[44:47], v[174:177], v[222:225], v[44:47]
	v_mfma_f32_16x16x32_bf16 v[40:43], v[190:193], v[222:225], v[40:43]
	v_mfma_f32_16x16x32_bf16 v[28:31], v[174:177], v[230:233], v[28:31]
	v_mfma_f32_16x16x32_bf16 v[24:27], v[190:193], v[230:233], v[24:27]
	v_mfma_f32_16x16x32_bf16 v[12:15], v[174:177], v[240:243], v[12:15]
	v_mfma_f32_16x16x32_bf16 v[8:11], v[190:193], v[240:243], v[8:11]
	v_mfma_f32_16x16x32_bf16 v[60:63], v[178:181], v[218:221], v[60:63]
	v_mfma_f32_16x16x32_bf16 v[56:59], v[194:197], v[218:221], v[56:59]
	v_mfma_f32_16x16x32_bf16 v[44:47], v[178:181], v[226:229], v[44:47]
	v_mfma_f32_16x16x32_bf16 v[40:43], v[194:197], v[226:229], v[40:43]
	v_mfma_f32_16x16x32_bf16 v[28:31], v[178:181], v[236:239], v[28:31]
	v_mfma_f32_16x16x32_bf16 v[24:27], v[194:197], v[236:239], v[24:27]
	v_mfma_f32_16x16x32_bf16 v[12:15], v[178:181], v[244:247], v[12:15]
	v_mfma_f32_16x16x32_bf16 v[8:11], v[194:197], v[244:247], v[8:11]
	s_setprio 0
	s_setprio 1
	v_mfma_f32_16x16x32_bf16 v[52:55], v[198:201], v[214:217], v[52:55]
	v_mfma_f32_16x16x32_bf16 v[48:51], v[206:209], v[214:217], v[48:51]
	v_mfma_f32_16x16x32_bf16 v[36:39], v[198:201], v[222:225], v[36:39]
	v_mfma_f32_16x16x32_bf16 v[32:35], v[206:209], v[222:225], v[32:35]
	v_mfma_f32_16x16x32_bf16 v[20:23], v[198:201], v[230:233], v[20:23]
	v_mfma_f32_16x16x32_bf16 v[16:19], v[206:209], v[230:233], v[16:19]
	v_mfma_f32_16x16x32_bf16 v[4:7], v[198:201], v[240:243], v[4:7]
	v_mfma_f32_16x16x32_bf16 v[0:3], v[206:209], v[240:243], v[0:3]
	v_mfma_f32_16x16x32_bf16 v[52:55], v[202:205], v[218:221], v[52:55]
	v_mfma_f32_16x16x32_bf16 v[48:51], v[210:213], v[218:221], v[48:51]
	v_mfma_f32_16x16x32_bf16 v[36:39], v[202:205], v[226:229], v[36:39]
	v_mfma_f32_16x16x32_bf16 v[32:35], v[210:213], v[226:229], v[32:35]
	v_mfma_f32_16x16x32_bf16 v[20:23], v[202:205], v[236:239], v[20:23]
	v_mfma_f32_16x16x32_bf16 v[16:19], v[210:213], v[236:239], v[16:19]
	v_mfma_f32_16x16x32_bf16 v[4:7], v[202:205], v[244:247], v[4:7]
	v_mfma_f32_16x16x32_bf16 v[0:3], v[210:213], v[244:247], v[0:3]
	s_setprio 0
	s_barrier
	s_add_i32 s59, s59, 2
	s_add_u32 s55, s55, 0x100
	s_addc_u32 s57, s57, 0
	s_add_u32 s66, s66, 0x100
	s_addc_u32 s67, s67, 0
	s_cmp_gt_u32 s59, 29
	s_cbranch_scc0 .LBB0_963
	s_and_b64 vcc, exec, s[52:53]
	s_cbranch_vccz .LBB0_966
	s_barrier
